# K-loop restart path shortened: setprio hoisted above the barrier and the redundant LDS wait after it removed in all five GEMM loops; loop placement kept
# baseline (speedup 1.0000x reference)
; #define PG8_STAGE(bufoff, gbase, voff) do { _Pragma("unroll") for (int _i = 0; _i < 2; ++_i) \
;         __builtin_amdgcn_global_load_lds((const unsigned*)((const char*)(gbase) + (voff)[_i]), (PG8_LAS unsigned*)(lds + (bufoff) + ldsw + _i * 8192), 16, 0, 0); } while (0)
; #define PG8_LDA(dst, b, h) do { _Pragma("unroll") for (int m = 0; m < 4; ++m) _Pragma("unroll") for (int k = 0; k < 2; ++k) dst[m][k] = *(const PG8_LAS bf16x8*)(lds + PG8_SA(b, h) + aoff + m * 2048 + k * 1024); } while (0)
; #define PG8_LDB(dst, b, h) do { _Pragma("unroll") for (int n = 0; n < 2; ++n) _Pragma("unroll") for (int k = 0; k < 2; ++k) dst[n][k] = *(const PG8_LAS bf16x8*)(lds + PG8_SB(b, h) + boff + n * 2048 + k * 1024); } while (0)
; #define PG8_MMA(ai, bj, At, Bt) do { __builtin_amdgcn_s_setprio(1); _Pragma("unroll") for (int m = 0; m < 4; ++m) _Pragma("unroll") for (int n = 0; n < 2; ++n) _Pragma("unroll") for (int k = 0; k < 2; ++k) \
;         acc[ai][bj][m][n] = __builtin_amdgcn_mfma_f32_16x16x32_bf16(Bt[n][k], At[m][k], acc[ai][bj][m][n], 0, 0, 0); __builtin_amdgcn_s_setprio(0); } while (0)
; #define PG8_WAIT_V(n) asm volatile("s_waitcnt vmcnt(" #n ")" ::: "memory")
; #define PG8_WAIT_L(n) asm volatile("s_waitcnt lgkmcnt(" #n ")" ::: "memory")
; #define PG8_BAR __builtin_amdgcn_s_barrier()
; #define PG8_SCHED __builtin_amdgcn_sched_barrier(0)
; template <class Epi, class Sched, bool ALIGN_EPI = false, bool SP2 = false>
; __device__ __forceinline__ void gemm_phase(PG8_LAS unsigned char* lds, const Gemm g, const Sched& S, const Epi& E) {
;     ...
;             PG8_LDB(B0, 0, 0); PG8_LDB(B1, 0, 1); PG8_SCHED; PG8_LDA(At, 0, 0); PG8_STAGE(PG8_SA(1, 1), a1 + hstep, voffA);
;             PG8_WAIT_V(8); PG8_WAIT_L(0); PG8_BAR; PG8_MMA(0, 0, At, B0); PG8_MMA(0, 1, At, B1); PG8_BAR; PG8_SCHED;
;             PG8_LDA(At, 0, 1); PG8_STAGE(PG8_SB(0, 0), b2, voffB); PG8_STAGE(PG8_SB(0, 1), b2 + hstep, voffB); PG8_STAGE(PG8_SA(0, 0), a2, voffA);
.LBB0_221:
	s_add_u32 s4, s0, 0xfff80080
	s_addc_u32 s5, s1, -1
	s_add_i32 s51, 0, 0x10000
	s_cmp_eq_u32 s50, 28
	s_cselect_b32 s29, s25, s5
	s_cselect_b32 s28, s46, s4
	v_add_u32_e32 v146, s51, v150
	s_cselect_b32 s5, s23, s49
	s_cselect_b32 s4, s47, s48
	s_add_i32 s54, 0, 0x14000
	ds_read_b128 v[138:141], v146
	ds_read_b128 v[142:145], v146 offset:1024
	ds_read_b128 v[164:167], v146 offset:2048
	ds_read_b128 v[168:171], v146 offset:3072
	v_add_u32_e32 v146, s54, v150
	ds_read_b128 v[172:175], v146
	ds_read_b128 v[176:179], v146 offset:1024
	ds_read_b128 v[180:183], v146 offset:2048
	ds_read_b128 v[184:187], v146 offset:3072
	v_lshl_add_u64 v[146:147], s[0:1], 0, v[134:135]
	s_add_i32 m0, s35, 0xc000
	ds_read_b128 v[188:191], v151
	ds_read_b128 v[192:195], v151 offset:1024
	ds_read_b128 v[196:199], v151 offset:2048
	ds_read_b128 v[200:203], v151 offset:3072
	ds_read_b128 v[204:207], v151 offset:4096
	ds_read_b128 v[208:211], v151 offset:5120
	ds_read_b128 v[212:215], v151 offset:6144
	ds_read_b128 v[216:219], v151 offset:7168
	global_load_lds_dwordx4 v[146:147], off
	v_lshl_add_u64 v[146:147], s[0:1], 0, v[136:137]
	s_add_i32 m0, s35, 0xe000
	s_nop 0
	global_load_lds_dwordx4 v[146:147], off
	s_waitcnt vmcnt(8)
	s_waitcnt lgkmcnt(0)
	s_setprio 1
	s_barrier
	v_mfma_f32_16x16x32_bf16 v[124:127], v[138:141], v[188:191], v[124:127]
	v_mfma_f32_16x16x32_bf16 v[120:123], v[164:167], v[188:191], v[120:123]
	v_mfma_f32_16x16x32_bf16 v[108:111], v[138:141], v[196:199], v[108:111]
	v_mfma_f32_16x16x32_bf16 v[104:107], v[164:167], v[196:199], v[104:107]
	v_mfma_f32_16x16x32_bf16 v[92:95], v[138:141], v[204:207], v[92:95]
	v_mfma_f32_16x16x32_bf16 v[88:91], v[164:167], v[204:207], v[88:91]
	v_mfma_f32_16x16x32_bf16 v[76:79], v[138:141], v[212:215], v[76:79]
	v_mfma_f32_16x16x32_bf16 v[72:75], v[164:167], v[212:215], v[72:75]
	v_mfma_f32_16x16x32_bf16 v[124:127], v[142:145], v[192:195], v[124:127]
	v_mfma_f32_16x16x32_bf16 v[120:123], v[168:171], v[192:195], v[120:123]
	v_mfma_f32_16x16x32_bf16 v[108:111], v[142:145], v[200:203], v[108:111]
	v_mfma_f32_16x16x32_bf16 v[104:107], v[168:171], v[200:203], v[104:107]
	v_mfma_f32_16x16x32_bf16 v[92:95], v[142:145], v[208:211], v[92:95]
	v_mfma_f32_16x16x32_bf16 v[88:91], v[168:171], v[208:211], v[88:91]
	v_mfma_f32_16x16x32_bf16 v[76:79], v[142:145], v[216:219], v[76:79]
	v_mfma_f32_16x16x32_bf16 v[72:75], v[168:171], v[216:219], v[72:75]
	s_setprio 0
	s_setprio 1
	v_mfma_f32_16x16x32_bf16 v[116:119], v[172:175], v[188:191], v[116:119]
	v_mfma_f32_16x16x32_bf16 v[112:115], v[180:183], v[188:191], v[112:115]
	v_mfma_f32_16x16x32_bf16 v[100:103], v[172:175], v[196:199], v[100:103]
	v_mfma_f32_16x16x32_bf16 v[96:99], v[180:183], v[196:199], v[96:99]
	v_mfma_f32_16x16x32_bf16 v[84:87], v[172:175], v[204:207], v[84:87]
	v_mfma_f32_16x16x32_bf16 v[80:83], v[180:183], v[204:207], v[80:83]
	v_mfma_f32_16x16x32_bf16 v[68:71], v[172:175], v[212:215], v[68:71]
	v_mfma_f32_16x16x32_bf16 v[64:67], v[180:183], v[212:215], v[64:67]
	v_mfma_f32_16x16x32_bf16 v[116:119], v[176:179], v[192:195], v[116:119]
	v_mfma_f32_16x16x32_bf16 v[112:115], v[184:187], v[192:195], v[112:115]
	v_mfma_f32_16x16x32_bf16 v[100:103], v[176:179], v[200:203], v[100:103]
	v_mfma_f32_16x16x32_bf16 v[96:99], v[184:187], v[200:203], v[96:99]
	v_mfma_f32_16x16x32_bf16 v[84:87], v[176:179], v[208:211], v[84:87]
	v_mfma_f32_16x16x32_bf16 v[80:83], v[184:187], v[208:211], v[80:83]
	v_mfma_f32_16x16x32_bf16 v[68:71], v[176:179], v[216:219], v[68:71]
	v_mfma_f32_16x16x32_bf16 v[64:67], v[184:187], v[216:219], v[64:67]
	s_setprio 0
	s_barrier
	s_add_i32 s51, s51, s30
	v_lshl_add_u64 v[146:147], s[4:5], 0, v[152:153]
	s_mov_b32 m0, s51
	ds_read_b128 v[188:191], v151 offset:16384
	ds_read_b128 v[192:195], v151 offset:17408
	ds_read_b128 v[196:199], v151 offset:18432
	ds_read_b128 v[200:203], v151 offset:19456
	ds_read_b128 v[204:207], v151 offset:20480
	ds_read_b128 v[208:211], v151 offset:21504
	ds_read_b128 v[212:215], v151 offset:22528
	ds_read_b128 v[216:219], v151 offset:23552
	global_load_lds_dwordx4 v[146:147], off
	s_add_i32 m0, s51, 0x2000
	s_add_u32 s52, s4, 0x80000
	v_lshl_add_u64 v[220:221], s[4:5], 0, v[128:129]
	s_addc_u32 s53, s5, 0
	s_add_i32 s51, s54, s30
	global_load_lds_dwordx4 v[220:221], off
	v_lshl_add_u64 v[222:223], s[52:53], 0, v[152:153]
	s_mov_b32 m0, s51
	v_lshl_add_u64 v[224:225], s[28:29], 0, v[130:131]
	global_load_lds_dwordx4 v[222:223], off
	v_lshl_add_u64 v[222:223], s[52:53], 0, v[128:129]
	s_add_i32 m0, s51, 0x2000
	s_nop 0
	global_load_lds_dwordx4 v[222:223], off
	v_lshl_add_u64 v[222:223], s[28:29], 0, v[132:133]
	s_mov_b32 m0, s35
	s_nop 0
	global_load_lds_dwordx4 v[222:223], off
	s_mov_b32 m0, s36
	s_nop 0
	global_load_lds_dwordx4 v[224:225], off
	s_waitcnt vmcnt(8)
	s_waitcnt lgkmcnt(0)
	s_setprio 1
	s_barrier
; #define PG8_STAGE(bufoff, gbase, voff) do { _Pragma("unroll") for (int _i = 0; _i < 2; ++_i) \
;         __builtin_amdgcn_global_load_lds((const unsigned*)((const char*)(gbase) + (voff)[_i]), (PG8_LAS unsigned*)(lds + (bufoff) + ldsw + _i * 8192), 16, 0, 0); } while (0)
; #define PG8_LDA(dst, b, h) do { _Pragma("unroll") for (int m = 0; m < 4; ++m) _Pragma("unroll") for (int k = 0; k < 2; ++k) dst[m][k] = *(const PG8_LAS bf16x8*)(lds + PG8_SA(b, h) + aoff + m * 2048 + k * 1024); } while (0)
; #define PG8_LDB(dst, b, h) do { _Pragma("unroll") for (int n = 0; n < 2; ++n) _Pragma("unroll") for (int k = 0; k < 2; ++k) dst[n][k] = *(const PG8_LAS bf16x8*)(lds + PG8_SB(b, h) + boff + n * 2048 + k * 1024); } while (0)
; #define PG8_MMA(ai, bj, At, Bt) do { __builtin_amdgcn_s_setprio(1); _Pragma("unroll") for (int m = 0; m < 4; ++m) _Pragma("unroll") for (int n = 0; n < 2; ++n) _Pragma("unroll") for (int k = 0; k < 2; ++k) \
;         acc[ai][bj][m][n] = __builtin_amdgcn_mfma_f32_16x16x32_bf16(Bt[n][k], At[m][k], acc[ai][bj][m][n], 0, 0, 0); __builtin_amdgcn_s_setprio(0); } while (0)
; #define PG8_WAIT_V(n) asm volatile("s_waitcnt vmcnt(" #n ")" ::: "memory")
; #define PG8_WAIT_L(n) asm volatile("s_waitcnt lgkmcnt(" #n ")" ::: "memory")
; #define PG8_BAR __builtin_amdgcn_s_barrier()
; #define PG8_SCHED __builtin_amdgcn_sched_barrier(0)
; template <class Epi, class Sched, bool ALIGN_EPI = false, bool SP2 = false>
; __device__ __forceinline__ void gemm_phase(PG8_LAS unsigned char* lds, const Gemm g, const Sched& S, const Epi& E) {
;     ...
;             PG8_WAIT_V(8); PG8_WAIT_L(0); PG8_BAR; PG8_MMA(1, 0, At, B0); PG8_MMA(1, 1, At, B1); PG8_BAR; PG8_SCHED;
;             PG8_LDB(B0, 1, 0); PG8_LDB(B1, 1, 1); PG8_SCHED; PG8_LDA(At, 1, 0); PG8_STAGE(PG8_SA(0, 1), a2 + hstep, voffA);
;             PG8_WAIT_V(8); PG8_WAIT_L(0); PG8_BAR; PG8_MMA(0, 0, At, B0); PG8_MMA(0, 1, At, B1); PG8_BAR; PG8_SCHED;
	v_mfma_f32_16x16x32_bf16 v[60:63], v[138:141], v[188:191], v[60:63]
	v_mfma_f32_16x16x32_bf16 v[56:59], v[164:167], v[188:191], v[56:59]
	v_mfma_f32_16x16x32_bf16 v[44:47], v[138:141], v[196:199], v[44:47]
	v_mfma_f32_16x16x32_bf16 v[40:43], v[164:167], v[196:199], v[40:43]
	v_mfma_f32_16x16x32_bf16 v[28:31], v[138:141], v[204:207], v[28:31]
	v_mfma_f32_16x16x32_bf16 v[24:27], v[164:167], v[204:207], v[24:27]
	v_mfma_f32_16x16x32_bf16 v[12:15], v[138:141], v[212:215], v[12:15]
	v_mfma_f32_16x16x32_bf16 v[8:11], v[164:167], v[212:215], v[8:11]
	v_mfma_f32_16x16x32_bf16 v[60:63], v[142:145], v[192:195], v[60:63]
	v_mfma_f32_16x16x32_bf16 v[56:59], v[168:171], v[192:195], v[56:59]
	v_mfma_f32_16x16x32_bf16 v[44:47], v[142:145], v[200:203], v[44:47]
	v_mfma_f32_16x16x32_bf16 v[40:43], v[168:171], v[200:203], v[40:43]
	v_mfma_f32_16x16x32_bf16 v[28:31], v[142:145], v[208:211], v[28:31]
	v_mfma_f32_16x16x32_bf16 v[24:27], v[168:171], v[208:211], v[24:27]
	v_mfma_f32_16x16x32_bf16 v[12:15], v[142:145], v[216:219], v[12:15]
	v_mfma_f32_16x16x32_bf16 v[8:11], v[168:171], v[216:219], v[8:11]
	s_setprio 0
	s_setprio 1
	v_mfma_f32_16x16x32_bf16 v[52:55], v[172:175], v[188:191], v[52:55]
	v_mfma_f32_16x16x32_bf16 v[48:51], v[180:183], v[188:191], v[48:51]
	v_mfma_f32_16x16x32_bf16 v[36:39], v[172:175], v[196:199], v[36:39]
	v_mfma_f32_16x16x32_bf16 v[32:35], v[180:183], v[196:199], v[32:35]
	v_mfma_f32_16x16x32_bf16 v[20:23], v[172:175], v[204:207], v[20:23]
	v_mfma_f32_16x16x32_bf16 v[16:19], v[180:183], v[204:207], v[16:19]
	v_mfma_f32_16x16x32_bf16 v[4:7], v[172:175], v[212:215], v[4:7]
	v_mfma_f32_16x16x32_bf16 v[0:3], v[180:183], v[212:215], v[0:3]
	v_mfma_f32_16x16x32_bf16 v[52:55], v[176:179], v[192:195], v[52:55]
	v_mfma_f32_16x16x32_bf16 v[48:51], v[184:187], v[192:195], v[48:51]
	v_mfma_f32_16x16x32_bf16 v[36:39], v[176:179], v[200:203], v[36:39]
	v_mfma_f32_16x16x32_bf16 v[32:35], v[184:187], v[200:203], v[32:35]
	v_mfma_f32_16x16x32_bf16 v[20:23], v[176:179], v[208:211], v[20:23]
	v_mfma_f32_16x16x32_bf16 v[16:19], v[184:187], v[208:211], v[16:19]
	v_mfma_f32_16x16x32_bf16 v[4:7], v[176:179], v[216:219], v[4:7]
	v_mfma_f32_16x16x32_bf16 v[0:3], v[184:187], v[216:219], v[0:3]
	s_setprio 0
	s_barrier
	s_add_i32 s51, 0, 0x18000
	s_add_i32 s52, 0, 0x1c000
	v_add_u32_e32 v168, s51, v150
	v_add_u32_e32 v184, s52, v150
	ds_read_b128 v[138:141], v168
	ds_read_b128 v[142:145], v168 offset:1024
	ds_read_b128 v[164:167], v168 offset:2048
	ds_read_b128 v[168:171], v168 offset:3072
	ds_read_b128 v[172:175], v184
	ds_read_b128 v[176:179], v184 offset:1024
	ds_read_b128 v[180:183], v184 offset:2048
	ds_read_b128 v[184:187], v184 offset:3072
	s_add_u32 s28, s28, 0x80000
	s_addc_u32 s29, s29, 0
	s_mov_b32 m0, s37
	v_lshl_add_u64 v[226:227], s[28:29], 0, v[132:133]
	ds_read_b128 v[188:191], v151 offset:32768
	ds_read_b128 v[192:195], v151 offset:33792
	ds_read_b128 v[196:199], v151 offset:34816
	ds_read_b128 v[200:203], v151 offset:35840
	ds_read_b128 v[204:207], v151 offset:36864
	ds_read_b128 v[208:211], v151 offset:37888
	ds_read_b128 v[212:215], v151 offset:38912
	ds_read_b128 v[216:219], v151 offset:39936
	global_load_lds_dwordx4 v[226:227], off
	v_lshl_add_u64 v[226:227], s[28:29], 0, v[130:131]
	s_mov_b32 m0, s38
	s_nop 0
	global_load_lds_dwordx4 v[226:227], off
	s_waitcnt vmcnt(8)
	s_waitcnt lgkmcnt(0)
	s_setprio 1
	s_barrier
	v_mfma_f32_16x16x32_bf16 v[124:127], v[138:141], v[188:191], v[124:127]
	v_mfma_f32_16x16x32_bf16 v[120:123], v[164:167], v[188:191], v[120:123]
	v_mfma_f32_16x16x32_bf16 v[108:111], v[138:141], v[196:199], v[108:111]
	v_mfma_f32_16x16x32_bf16 v[104:107], v[164:167], v[196:199], v[104:107]
	v_mfma_f32_16x16x32_bf16 v[92:95], v[138:141], v[204:207], v[92:95]
	v_mfma_f32_16x16x32_bf16 v[88:91], v[164:167], v[204:207], v[88:91]
	v_mfma_f32_16x16x32_bf16 v[76:79], v[138:141], v[212:215], v[76:79]
	v_mfma_f32_16x16x32_bf16 v[72:75], v[164:167], v[212:215], v[72:75]
	v_mfma_f32_16x16x32_bf16 v[124:127], v[142:145], v[192:195], v[124:127]
	v_mfma_f32_16x16x32_bf16 v[120:123], v[168:171], v[192:195], v[120:123]
	v_mfma_f32_16x16x32_bf16 v[108:111], v[142:145], v[200:203], v[108:111]
	v_mfma_f32_16x16x32_bf16 v[104:107], v[168:171], v[200:203], v[104:107]
	v_mfma_f32_16x16x32_bf16 v[92:95], v[142:145], v[208:211], v[92:95]
	v_mfma_f32_16x16x32_bf16 v[88:91], v[168:171], v[208:211], v[88:91]
	v_mfma_f32_16x16x32_bf16 v[76:79], v[142:145], v[216:219], v[76:79]
	v_mfma_f32_16x16x32_bf16 v[72:75], v[168:171], v[216:219], v[72:75]
	s_setprio 0
	s_setprio 1
	v_mfma_f32_16x16x32_bf16 v[116:119], v[172:175], v[188:191], v[116:119]
	v_mfma_f32_16x16x32_bf16 v[112:115], v[180:183], v[188:191], v[112:115]
	v_mfma_f32_16x16x32_bf16 v[100:103], v[172:175], v[196:199], v[100:103]
	v_mfma_f32_16x16x32_bf16 v[96:99], v[180:183], v[196:199], v[96:99]
	v_mfma_f32_16x16x32_bf16 v[84:87], v[172:175], v[204:207], v[84:87]
	v_mfma_f32_16x16x32_bf16 v[80:83], v[180:183], v[204:207], v[80:83]
	v_mfma_f32_16x16x32_bf16 v[68:71], v[172:175], v[212:215], v[68:71]
	v_mfma_f32_16x16x32_bf16 v[64:67], v[180:183], v[212:215], v[64:67]
	v_mfma_f32_16x16x32_bf16 v[116:119], v[176:179], v[192:195], v[116:119]
	v_mfma_f32_16x16x32_bf16 v[112:115], v[184:187], v[192:195], v[112:115]
	v_mfma_f32_16x16x32_bf16 v[100:103], v[176:179], v[200:203], v[100:103]
	v_mfma_f32_16x16x32_bf16 v[96:99], v[184:187], v[200:203], v[96:99]
	v_mfma_f32_16x16x32_bf16 v[84:87], v[176:179], v[208:211], v[84:87]
	v_mfma_f32_16x16x32_bf16 v[80:83], v[184:187], v[208:211], v[80:83]
	v_mfma_f32_16x16x32_bf16 v[68:71], v[176:179], v[216:219], v[68:71]
	v_mfma_f32_16x16x32_bf16 v[64:67], v[184:187], v[216:219], v[64:67]
	s_setprio 0
	s_barrier
; #define PG8_STAGE(bufoff, gbase, voff) do { _Pragma("unroll") for (int _i = 0; _i < 2; ++_i) \
;         __builtin_amdgcn_global_load_lds((const unsigned*)((const char*)(gbase) + (voff)[_i]), (PG8_LAS unsigned*)(lds + (bufoff) + ldsw + _i * 8192), 16, 0, 0); } while (0)
; #define PG8_LDA(dst, b, h) do { _Pragma("unroll") for (int m = 0; m < 4; ++m) _Pragma("unroll") for (int k = 0; k < 2; ++k) dst[m][k] = *(const PG8_LAS bf16x8*)(lds + PG8_SA(b, h) + aoff + m * 2048 + k * 1024); } while (0)
; #define PG8_MMA(ai, bj, At, Bt) do { __builtin_amdgcn_s_setprio(1); _Pragma("unroll") for (int m = 0; m < 4; ++m) _Pragma("unroll") for (int n = 0; n < 2; ++n) _Pragma("unroll") for (int k = 0; k < 2; ++k) \
;         acc[ai][bj][m][n] = __builtin_amdgcn_mfma_f32_16x16x32_bf16(Bt[n][k], At[m][k], acc[ai][bj][m][n], 0, 0, 0); __builtin_amdgcn_s_setprio(0); } while (0)
; #define PG8_WAIT_V(n) asm volatile("s_waitcnt vmcnt(" #n ")" ::: "memory")
; #define PG8_WAIT_L(n) asm volatile("s_waitcnt lgkmcnt(" #n ")" ::: "memory")
; #define PG8_BAR __builtin_amdgcn_s_barrier()
; #define PG8_SCHED __builtin_amdgcn_sched_barrier(0)
; template <class Epi, class Sched, bool ALIGN_EPI = false, bool SP2 = false>
; __device__ __forceinline__ void gemm_phase(PG8_LAS unsigned char* lds, const Gemm g, const Sched& S, const Epi& E) {
;     ...
;             PG8_LDA(At, 1, 1); PG8_STAGE(PG8_SB(1, 0), b3, voffB); PG8_STAGE(PG8_SB(1, 1), b3 + hstep, voffB); PG8_STAGE(PG8_SA(1, 0), a3, voffA);
;             PG8_WAIT_V(8); PG8_WAIT_L(0); PG8_BAR; PG8_MMA(1, 0, At, B0); PG8_MMA(1, 1, At, B1); PG8_BAR; PG8_SCHED;
;     ...
;         if constexpr (ALIGN_EPI) { if (wr == 0) PG8_BAR; }
	s_add_i32 s28, s51, s30
	v_lshl_add_u64 v[146:147], v[146:147], 0, s[74:75]
	s_mov_b32 m0, s28
	ds_read_b128 v[188:191], v151 offset:49152
	ds_read_b128 v[192:195], v151 offset:50176
	ds_read_b128 v[196:199], v151 offset:51200
	ds_read_b128 v[200:203], v151 offset:52224
	ds_read_b128 v[204:207], v151 offset:53248
	ds_read_b128 v[208:211], v151 offset:54272
	ds_read_b128 v[212:215], v151 offset:55296
	ds_read_b128 v[216:219], v151 offset:56320
	global_load_lds_dwordx4 v[146:147], off
	s_add_i32 m0, s28, 0x2000
	s_add_u32 s4, s4, 0x80080
	v_lshl_add_u64 v[146:147], v[220:221], 0, s[74:75]
	s_addc_u32 s5, s5, 0
	s_add_i32 s28, s52, s30
	global_load_lds_dwordx4 v[146:147], off
	v_lshl_add_u64 v[146:147], s[4:5], 0, v[152:153]
	s_mov_b32 m0, s28
	s_nop 0
	global_load_lds_dwordx4 v[146:147], off
	v_lshl_add_u64 v[146:147], s[4:5], 0, v[128:129]
	s_add_i32 m0, s28, 0x2000
	s_nop 0
	global_load_lds_dwordx4 v[146:147], off
	v_lshl_add_u64 v[146:147], v[222:223], 0, s[74:75]
	s_mov_b32 m0, s42
	s_nop 0
	global_load_lds_dwordx4 v[146:147], off
	v_lshl_add_u64 v[146:147], v[224:225], 0, s[74:75]
	s_mov_b32 m0, s43
	s_nop 0
	global_load_lds_dwordx4 v[146:147], off
	s_waitcnt vmcnt(8)
	s_waitcnt lgkmcnt(0)
	s_setprio 1
	s_barrier
	v_mfma_f32_16x16x32_bf16 v[60:63], v[138:141], v[188:191], v[60:63]
	v_mfma_f32_16x16x32_bf16 v[56:59], v[164:167], v[188:191], v[56:59]
	v_mfma_f32_16x16x32_bf16 v[44:47], v[138:141], v[196:199], v[44:47]
	v_mfma_f32_16x16x32_bf16 v[40:43], v[164:167], v[196:199], v[40:43]
	v_mfma_f32_16x16x32_bf16 v[28:31], v[138:141], v[204:207], v[28:31]
	v_mfma_f32_16x16x32_bf16 v[24:27], v[164:167], v[204:207], v[24:27]
	v_mfma_f32_16x16x32_bf16 v[12:15], v[138:141], v[212:215], v[12:15]
	v_mfma_f32_16x16x32_bf16 v[8:11], v[164:167], v[212:215], v[8:11]
	v_mfma_f32_16x16x32_bf16 v[60:63], v[142:145], v[192:195], v[60:63]
	v_mfma_f32_16x16x32_bf16 v[56:59], v[168:171], v[192:195], v[56:59]
	v_mfma_f32_16x16x32_bf16 v[44:47], v[142:145], v[200:203], v[44:47]
	v_mfma_f32_16x16x32_bf16 v[40:43], v[168:171], v[200:203], v[40:43]
	v_mfma_f32_16x16x32_bf16 v[28:31], v[142:145], v[208:211], v[28:31]
	v_mfma_f32_16x16x32_bf16 v[24:27], v[168:171], v[208:211], v[24:27]
	v_mfma_f32_16x16x32_bf16 v[12:15], v[142:145], v[216:219], v[12:15]
	v_mfma_f32_16x16x32_bf16 v[8:11], v[168:171], v[216:219], v[8:11]
	s_setprio 0
	s_setprio 1
	v_mfma_f32_16x16x32_bf16 v[52:55], v[172:175], v[188:191], v[52:55]
	v_mfma_f32_16x16x32_bf16 v[48:51], v[180:183], v[188:191], v[48:51]
	v_mfma_f32_16x16x32_bf16 v[36:39], v[172:175], v[196:199], v[36:39]
	v_mfma_f32_16x16x32_bf16 v[32:35], v[180:183], v[196:199], v[32:35]
	v_mfma_f32_16x16x32_bf16 v[20:23], v[172:175], v[204:207], v[20:23]
	v_mfma_f32_16x16x32_bf16 v[16:19], v[180:183], v[204:207], v[16:19]
	v_mfma_f32_16x16x32_bf16 v[4:7], v[172:175], v[212:215], v[4:7]
	v_mfma_f32_16x16x32_bf16 v[0:3], v[180:183], v[212:215], v[0:3]
	v_mfma_f32_16x16x32_bf16 v[52:55], v[176:179], v[192:195], v[52:55]
	v_mfma_f32_16x16x32_bf16 v[48:51], v[184:187], v[192:195], v[48:51]
	v_mfma_f32_16x16x32_bf16 v[36:39], v[176:179], v[200:203], v[36:39]
	v_mfma_f32_16x16x32_bf16 v[32:35], v[184:187], v[200:203], v[32:35]
	v_mfma_f32_16x16x32_bf16 v[20:23], v[176:179], v[208:211], v[20:23]
	v_mfma_f32_16x16x32_bf16 v[16:19], v[184:187], v[208:211], v[16:19]
	v_mfma_f32_16x16x32_bf16 v[4:7], v[176:179], v[216:219], v[4:7]
	v_mfma_f32_16x16x32_bf16 v[0:3], v[184:187], v[216:219], v[0:3]
	s_setprio 0
	s_barrier
	s_add_i32 s50, s50, 2
	s_add_u32 s0, s0, 0x100
	s_addc_u32 s1, s1, 0
	s_add_u32 s48, s48, 0x100
	s_addc_u32 s49, s49, 0
	s_cmp_gt_u32 s50, 29
	s_cbranch_scc0 .LBB0_221
	s_and_b64 vcc, exec, s[20:21]
	s_cbranch_vccz .LBB0_224
	s_barrier

; #define PG8_STAGE(bufoff, gbase, voff) do { _Pragma("unroll") for (int _i = 0; _i < 2; ++_i) \
;         __builtin_amdgcn_global_load_lds((const unsigned*)((const char*)(gbase) + (voff)[_i]), (PG8_LAS unsigned*)(lds + (bufoff) + ldsw + _i * 8192), 16, 0, 0); } while (0)
; #define PG8_WAIT_V(n) asm volatile("s_waitcnt vmcnt(" #n ")" ::: "memory")
; #define PG8_BAR __builtin_amdgcn_s_barrier()
; template <class Epi, class Sched, bool ALIGN_EPI = false, bool SP2 = false>
; __device__ __forceinline__ void gemm_phase(PG8_LAS unsigned char* lds, const Gemm g, const Sched& S, const Epi& E) {
;     ...
;         PG8_WAIT_V(2); PG8_BAR;
;         PG8_STAGE(PG8_SB(1, 0), cB + kstep, voffB); PG8_STAGE(PG8_SA(1, 0), cA + kstep, voffA); PG8_STAGE(PG8_SB(1, 1), cB + hstep + kstep, voffB);
;         PG8_WAIT_V(6); PG8_BAR;
; __global__ void __launch_bounds__(512, 2) fwd_kernel(Args a) {
;     ...
;                 EpiEven E{Qb, Kb, Vb, GB, Zb, cosT, sinT, out + O_KP + (size_t)j * 131072, out + O_VP + (size_t)j * 131072, out + O_CP + (size_t)j * 8192, PS, RS};
.LBB0_437:
	s_add_u32 s18, s14, 0x1a600000
	s_addc_u32 s19, s15, 0
	s_add_u32 s20, s14, 0x1ba00000
	s_addc_u32 s21, s15, 0
	s_add_u32 s22, s14, 0x1be00000
	s_addc_u32 s23, s15, 0
	s_add_u32 s24, s14, 0x1ce00000
	s_addc_u32 s25, s15, 0
	s_add_u32 s26, s14, 0x2e200000
	s_addc_u32 s27, s15, 0
	s_add_u32 s28, s14, 0x2e500000
	s_addc_u32 s29, s15, 0
	s_add_u32 s30, s14, 0x2e300000
	s_addc_u32 s31, s15, 0
	s_add_u32 s34, s14, 0x2e340000
	s_addc_u32 s35, s15, 0
	s_lshl_b64 s[36:37], s[72:73], 19
	s_add_u32 s3, s12, s36
	s_addc_u32 s33, s13, s37
	s_add_u32 s36, s3, 0x4140000
	s_addc_u32 s37, s33, 0
	s_lshl_b64 s[38:39], s[72:73], 15
	s_add_u32 s9, s12, s38
	s_addc_u32 s39, s13, s39
	s_add_u32 s38, s9, 0x4240000
	s_addc_u32 s39, s39, 0
	s_and_b32 s7, s7, 3
	s_add_i32 m0, s55, 0x18000
	v_lshl_add_u64 v[6:7], v[6:7], 0, s[74:75]
	s_mov_b64 s[86:87], s[72:73]
	s_lshl_b32 s70, s8, 6
	s_lshl_b32 s40, s8, 13
	s_lshl_b32 s71, s7, 5
	s_lshl_b32 s41, s7, 12
	s_waitcnt vmcnt(2)
	s_barrier
	global_load_lds_dwordx4 v[6:7], off
	v_lshl_add_u64 v[4:5], v[4:5], 0, s[74:75]
	s_add_i32 m0, s55, 0x1a000
	s_add_i32 s72, s55, 0x8000
	s_add_i32 s73, s55, 0xa000
	global_load_lds_dwordx4 v[4:5], off
	v_lshl_add_u64 v[0:1], v[0:1], 0, s[74:75]
	s_mov_b32 m0, s72
	s_add_u32 s8, s4, 0x80080
	global_load_lds_dwordx4 v[0:1], off
	v_lshl_add_u64 v[0:1], v[2:3], 0, s[74:75]
	s_mov_b32 m0, s73
	s_addc_u32 s9, s5, 0
	global_load_lds_dwordx4 v[0:1], off
	s_add_i32 m0, s55, 0x1c000
	v_lshl_add_u64 v[0:1], s[8:9], 0, v[166:167]
	global_load_lds_dwordx4 v[0:1], off
	v_lshl_add_u64 v[0:1], s[8:9], 0, v[170:171]
	s_add_i32 m0, s55, 0x1e000
	v_bfe_u32 v191, v8, 4, 2
	global_load_lds_dwordx4 v[0:1], off
	v_and_b32_e32 v190, 15, v8
	v_lshlrev_b32_e32 v0, 4, v191
	v_lshlrev_b32_e32 v1, 2, v8
	s_or_b32 s74, s71, 0xfffffb00
	v_lshl_or_b32 v0, v190, 6, v0
	v_and_b32_e32 v1, 32, v1
	s_cmpk_lt_u32 s6, 0x100
	v_bitop3_b32 v2, v0, s40, v1 bitop3:0xde
	v_bitop3_b32 v192, v0, s41, v1 bitop3:0xde
	s_cselect_b64 s[40:41], -1, 0
	s_and_b32 s77, s6, 0xc0
	s_or_b32 s75, s71, 0xfffffa00
	s_lshl_b32 s76, s7, 6
	s_or_b32 s78, s77, 0x400
	s_or_b32 s79, s77, 0x420
	s_lshl_b32 s6, s7, 7
	v_lshlrev_b32_e32 v0, 15, v9
	s_add_u32 s6, s14, s6
	v_and_b32_e32 v0, 0xffff0000, v0
	s_addc_u32 s8, s15, 0
	v_lshl_add_u32 v0, v10, 12, v0
	v_and_b32_e32 v1, 1, v9
	s_add_u32 s42, s6, 0x1b600000
	v_lshl_or_b32 v0, v1, 6, v0
	s_addc_u32 s43, s8, 0
	s_lshl_b32 s6, s7, 8
	v_lshl_add_u32 v172, v11, 1, v0
	v_lshlrev_b32_e32 v0, 15, v12
	s_add_u32 s3, s3, s6
	v_and_b32_e32 v0, 0xffff0000, v0
	s_waitcnt vmcnt(6)
	s_addc_u32 s6, s33, 0
	v_lshl_add_u32 v0, v13, 12, v0
	v_and_b32_e32 v1, 1, v12
	s_add_u32 s44, s3, 0x4040000
	v_lshl_or_b32 v0, v1, 6, v0
	s_addc_u32 s45, s6, 0
	v_mov_b32_e32 v173, v153
	v_lshl_add_u32 v174, v14, 1, v0
	v_mov_b32_e32 v175, v153
	s_mov_b32 s80, 0
	v_add_u32_e32 v193, 0, v2
	s_barrier
	s_branch .LBB0_440
	s_nop 0
	s_nop 0
	s_nop 0
	s_nop 0

; #define PG8_STAGE(bufoff, gbase, voff) do { _Pragma("unroll") for (int _i = 0; _i < 2; ++_i) \
;         __builtin_amdgcn_global_load_lds((const unsigned*)((const char*)(gbase) + (voff)[_i]), (PG8_LAS unsigned*)(lds + (bufoff) + ldsw + _i * 8192), 16, 0, 0); } while (0)
; #define PG8_LDA(dst, b, h) do { _Pragma("unroll") for (int m = 0; m < 4; ++m) _Pragma("unroll") for (int k = 0; k < 2; ++k) dst[m][k] = *(const PG8_LAS bf16x8*)(lds + PG8_SA(b, h) + aoff + m * 2048 + k * 1024); } while (0)
; #define PG8_LDB(dst, b, h) do { _Pragma("unroll") for (int n = 0; n < 2; ++n) _Pragma("unroll") for (int k = 0; k < 2; ++k) dst[n][k] = *(const PG8_LAS bf16x8*)(lds + PG8_SB(b, h) + boff + n * 2048 + k * 1024); } while (0)
; #define PG8_MMA(ai, bj, At, Bt) do { __builtin_amdgcn_s_setprio(1); _Pragma("unroll") for (int m = 0; m < 4; ++m) _Pragma("unroll") for (int n = 0; n < 2; ++n) _Pragma("unroll") for (int k = 0; k < 2; ++k) \
;         acc[ai][bj][m][n] = __builtin_amdgcn_mfma_f32_16x16x32_bf16(Bt[n][k], At[m][k], acc[ai][bj][m][n], 0, 0, 0); __builtin_amdgcn_s_setprio(0); } while (0)
; #define PG8_WAIT_V(n) asm volatile("s_waitcnt vmcnt(" #n ")" ::: "memory")
; #define PG8_WAIT_L(n) asm volatile("s_waitcnt lgkmcnt(" #n ")" ::: "memory")
; #define PG8_BAR __builtin_amdgcn_s_barrier()
; #define PG8_SCHED __builtin_amdgcn_sched_barrier(0)
; template <class Epi, class Sched, bool ALIGN_EPI = false, bool SP2 = false>
; __device__ __forceinline__ void gemm_phase(PG8_LAS unsigned char* lds, const Gemm g, const Sched& S, const Epi& E) {
;     ...
;             PG8_LDB(B0, 0, 0); PG8_LDB(B1, 0, 1); PG8_SCHED; PG8_LDA(At, 0, 0); PG8_STAGE(PG8_SA(1, 1), a1 + hstep, voffA);
;             PG8_WAIT_V(8); PG8_WAIT_L(0); PG8_BAR; PG8_MMA(0, 0, At, B0); PG8_MMA(0, 1, At, B1); PG8_BAR; PG8_SCHED;
;             PG8_LDA(At, 0, 1); PG8_STAGE(PG8_SB(0, 0), b2, voffB); PG8_STAGE(PG8_SB(0, 1), b2 + hstep, voffB); PG8_STAGE(PG8_SA(0, 0), a2, voffA);
.LBB0_447:
	s_add_u32 s4, s0, 0xfff80080
	s_addc_u32 s5, s1, -1
	s_add_i32 s59, 0, 0x10000
	s_cmp_eq_u32 s58, 28
	s_cselect_b32 s9, s3, s5
	s_cselect_b32 s8, s33, s4
	s_cselect_b32 s5, s47, s57
	s_cselect_b32 s4, s49, s56
	s_add_i32 s81, 0, 0x14000
	v_add_u32_e32 v140, s59, v192
	v_add_u32_e32 v152, s81, v192
	ds_read_b128 v[128:131], v140
	ds_read_b128 v[132:135], v140 offset:1024
	ds_read_b128 v[136:139], v140 offset:2048
	ds_read_b128 v[140:143], v140 offset:3072
	ds_read_b128 v[144:147], v152
	ds_read_b128 v[148:151], v152 offset:1024
	ds_read_b128 v[176:179], v152 offset:2048
	ds_read_b128 v[180:183], v152 offset:3072
	v_lshl_add_u64 v[188:189], s[0:1], 0, v[172:173]
	s_add_i32 m0, s55, 0xc000
	ds_read_b128 v[184:187], v193
	ds_read_b128 v[194:197], v193 offset:1024
	ds_read_b128 v[198:201], v193 offset:2048
	ds_read_b128 v[202:205], v193 offset:3072
	ds_read_b128 v[206:209], v193 offset:4096
	ds_read_b128 v[210:213], v193 offset:5120
	ds_read_b128 v[214:217], v193 offset:6144
	ds_read_b128 v[218:221], v193 offset:7168
	global_load_lds_dwordx4 v[188:189], off
	v_lshl_add_u64 v[188:189], s[0:1], 0, v[174:175]
	s_add_i32 m0, s55, 0xe000
	s_nop 0
	global_load_lds_dwordx4 v[188:189], off
	s_waitcnt vmcnt(8)
	s_waitcnt lgkmcnt(0)
	s_setprio 1
	s_barrier
	v_mfma_f32_16x16x32_bf16 v[28:31], v[128:131], v[184:187], v[28:31]
	v_mfma_f32_16x16x32_bf16 v[24:27], v[136:139], v[184:187], v[24:27]
	v_mfma_f32_16x16x32_bf16 v[12:15], v[128:131], v[198:201], v[12:15]
	v_mfma_f32_16x16x32_bf16 v[8:11], v[136:139], v[198:201], v[8:11]
	v_mfma_f32_16x16x32_bf16 v[124:127], v[128:131], v[206:209], v[124:127]
	v_mfma_f32_16x16x32_bf16 v[120:123], v[136:139], v[206:209], v[120:123]
	v_mfma_f32_16x16x32_bf16 v[108:111], v[128:131], v[214:217], v[108:111]
	v_mfma_f32_16x16x32_bf16 v[104:107], v[136:139], v[214:217], v[104:107]
	v_mfma_f32_16x16x32_bf16 v[28:31], v[132:135], v[194:197], v[28:31]
	v_mfma_f32_16x16x32_bf16 v[24:27], v[140:143], v[194:197], v[24:27]
	v_mfma_f32_16x16x32_bf16 v[12:15], v[132:135], v[202:205], v[12:15]
	v_mfma_f32_16x16x32_bf16 v[8:11], v[140:143], v[202:205], v[8:11]
	v_mfma_f32_16x16x32_bf16 v[124:127], v[132:135], v[210:213], v[124:127]
	v_mfma_f32_16x16x32_bf16 v[120:123], v[140:143], v[210:213], v[120:123]
	v_mfma_f32_16x16x32_bf16 v[108:111], v[132:135], v[218:221], v[108:111]
	v_mfma_f32_16x16x32_bf16 v[104:107], v[140:143], v[218:221], v[104:107]
	s_setprio 0
	s_setprio 1
	v_mfma_f32_16x16x32_bf16 v[20:23], v[144:147], v[184:187], v[20:23]
	v_mfma_f32_16x16x32_bf16 v[16:19], v[176:179], v[184:187], v[16:19]
	v_mfma_f32_16x16x32_bf16 v[4:7], v[144:147], v[198:201], v[4:7]
	v_mfma_f32_16x16x32_bf16 v[0:3], v[176:179], v[198:201], v[0:3]
	v_mfma_f32_16x16x32_bf16 v[116:119], v[144:147], v[206:209], v[116:119]
	v_mfma_f32_16x16x32_bf16 v[112:115], v[176:179], v[206:209], v[112:115]
	v_mfma_f32_16x16x32_bf16 v[100:103], v[144:147], v[214:217], v[100:103]
	v_mfma_f32_16x16x32_bf16 v[96:99], v[176:179], v[214:217], v[96:99]
	v_mfma_f32_16x16x32_bf16 v[20:23], v[148:151], v[194:197], v[20:23]
	v_mfma_f32_16x16x32_bf16 v[16:19], v[180:183], v[194:197], v[16:19]
	v_mfma_f32_16x16x32_bf16 v[4:7], v[148:151], v[202:205], v[4:7]
	v_mfma_f32_16x16x32_bf16 v[0:3], v[180:183], v[202:205], v[0:3]
	v_mfma_f32_16x16x32_bf16 v[116:119], v[148:151], v[210:213], v[116:119]
	v_mfma_f32_16x16x32_bf16 v[112:115], v[180:183], v[210:213], v[112:115]
	v_mfma_f32_16x16x32_bf16 v[100:103], v[148:151], v[218:221], v[100:103]
	v_mfma_f32_16x16x32_bf16 v[96:99], v[180:183], v[218:221], v[96:99]
	s_setprio 0
	s_barrier
	s_add_i32 s59, s59, s66
	v_lshl_add_u64 v[188:189], s[4:5], 0, v[166:167]
	s_mov_b32 m0, s59
	ds_read_b128 v[184:187], v193 offset:16384
	ds_read_b128 v[194:197], v193 offset:17408
	ds_read_b128 v[198:201], v193 offset:18432
	ds_read_b128 v[202:205], v193 offset:19456
	ds_read_b128 v[206:209], v193 offset:20480
	ds_read_b128 v[210:213], v193 offset:21504
	ds_read_b128 v[214:217], v193 offset:22528
	ds_read_b128 v[218:221], v193 offset:23552
	global_load_lds_dwordx4 v[188:189], off
	s_add_i32 m0, s59, 0x2000
	s_add_u32 s60, s4, 0x80000
	v_lshl_add_u64 v[222:223], s[4:5], 0, v[170:171]
	s_addc_u32 s61, s5, 0
	s_add_i32 s59, s81, s66
	global_load_lds_dwordx4 v[222:223], off
	v_lshl_add_u64 v[224:225], s[60:61], 0, v[166:167]
	s_mov_b32 m0, s59
	v_lshl_add_u64 v[226:227], s[8:9], 0, v[168:169]
	global_load_lds_dwordx4 v[224:225], off
	v_lshl_add_u64 v[224:225], s[60:61], 0, v[170:171]
	s_add_i32 m0, s59, 0x2000
	s_nop 0
	global_load_lds_dwordx4 v[224:225], off
	v_lshl_add_u64 v[224:225], s[8:9], 0, v[164:165]
	s_mov_b32 m0, s55
	s_nop 0
	global_load_lds_dwordx4 v[224:225], off
	s_mov_b32 m0, s67
	s_nop 0
	global_load_lds_dwordx4 v[226:227], off
	s_waitcnt vmcnt(8)
	s_waitcnt lgkmcnt(0)
	s_setprio 1
	s_barrier
; #define PG8_STAGE(bufoff, gbase, voff) do { _Pragma("unroll") for (int _i = 0; _i < 2; ++_i) \
;         __builtin_amdgcn_global_load_lds((const unsigned*)((const char*)(gbase) + (voff)[_i]), (PG8_LAS unsigned*)(lds + (bufoff) + ldsw + _i * 8192), 16, 0, 0); } while (0)
; #define PG8_LDA(dst, b, h) do { _Pragma("unroll") for (int m = 0; m < 4; ++m) _Pragma("unroll") for (int k = 0; k < 2; ++k) dst[m][k] = *(const PG8_LAS bf16x8*)(lds + PG8_SA(b, h) + aoff + m * 2048 + k * 1024); } while (0)
; #define PG8_LDB(dst, b, h) do { _Pragma("unroll") for (int n = 0; n < 2; ++n) _Pragma("unroll") for (int k = 0; k < 2; ++k) dst[n][k] = *(const PG8_LAS bf16x8*)(lds + PG8_SB(b, h) + boff + n * 2048 + k * 1024); } while (0)
; #define PG8_MMA(ai, bj, At, Bt) do { __builtin_amdgcn_s_setprio(1); _Pragma("unroll") for (int m = 0; m < 4; ++m) _Pragma("unroll") for (int n = 0; n < 2; ++n) _Pragma("unroll") for (int k = 0; k < 2; ++k) \
;         acc[ai][bj][m][n] = __builtin_amdgcn_mfma_f32_16x16x32_bf16(Bt[n][k], At[m][k], acc[ai][bj][m][n], 0, 0, 0); __builtin_amdgcn_s_setprio(0); } while (0)
; #define PG8_WAIT_V(n) asm volatile("s_waitcnt vmcnt(" #n ")" ::: "memory")
; #define PG8_WAIT_L(n) asm volatile("s_waitcnt lgkmcnt(" #n ")" ::: "memory")
; #define PG8_BAR __builtin_amdgcn_s_barrier()
; #define PG8_SCHED __builtin_amdgcn_sched_barrier(0)
; template <class Epi, class Sched, bool ALIGN_EPI = false, bool SP2 = false>
; __device__ __forceinline__ void gemm_phase(PG8_LAS unsigned char* lds, const Gemm g, const Sched& S, const Epi& E) {
;     ...
;             PG8_WAIT_V(8); PG8_WAIT_L(0); PG8_BAR; PG8_MMA(1, 0, At, B0); PG8_MMA(1, 1, At, B1); PG8_BAR; PG8_SCHED;
;             PG8_LDB(B0, 1, 0); PG8_LDB(B1, 1, 1); PG8_SCHED; PG8_LDA(At, 1, 0); PG8_STAGE(PG8_SA(0, 1), a2 + hstep, voffA);
;             PG8_WAIT_V(8); PG8_WAIT_L(0); PG8_BAR; PG8_MMA(0, 0, At, B0); PG8_MMA(0, 1, At, B1); PG8_BAR; PG8_SCHED;
	v_mfma_f32_16x16x32_bf16 v[92:95], v[128:131], v[184:187], v[92:95]
	v_mfma_f32_16x16x32_bf16 v[88:91], v[136:139], v[184:187], v[88:91]
	v_mfma_f32_16x16x32_bf16 v[76:79], v[128:131], v[198:201], v[76:79]
	v_mfma_f32_16x16x32_bf16 v[72:75], v[136:139], v[198:201], v[72:75]
	v_mfma_f32_16x16x32_bf16 v[60:63], v[128:131], v[206:209], v[60:63]
	v_mfma_f32_16x16x32_bf16 v[56:59], v[136:139], v[206:209], v[56:59]
	v_mfma_f32_16x16x32_bf16 v[44:47], v[128:131], v[214:217], v[44:47]
	v_mfma_f32_16x16x32_bf16 v[40:43], v[136:139], v[214:217], v[40:43]
	v_mfma_f32_16x16x32_bf16 v[92:95], v[132:135], v[194:197], v[92:95]
	v_mfma_f32_16x16x32_bf16 v[88:91], v[140:143], v[194:197], v[88:91]
	v_mfma_f32_16x16x32_bf16 v[76:79], v[132:135], v[202:205], v[76:79]
	v_mfma_f32_16x16x32_bf16 v[72:75], v[140:143], v[202:205], v[72:75]
	v_mfma_f32_16x16x32_bf16 v[60:63], v[132:135], v[210:213], v[60:63]
	v_mfma_f32_16x16x32_bf16 v[56:59], v[140:143], v[210:213], v[56:59]
	v_mfma_f32_16x16x32_bf16 v[44:47], v[132:135], v[218:221], v[44:47]
	v_mfma_f32_16x16x32_bf16 v[40:43], v[140:143], v[218:221], v[40:43]
	s_setprio 0
	s_setprio 1
	v_mfma_f32_16x16x32_bf16 v[84:87], v[144:147], v[184:187], v[84:87]
	v_mfma_f32_16x16x32_bf16 v[80:83], v[176:179], v[184:187], v[80:83]
	v_mfma_f32_16x16x32_bf16 v[68:71], v[144:147], v[198:201], v[68:71]
	v_mfma_f32_16x16x32_bf16 v[64:67], v[176:179], v[198:201], v[64:67]
	v_mfma_f32_16x16x32_bf16 v[52:55], v[144:147], v[206:209], v[52:55]
	v_mfma_f32_16x16x32_bf16 v[48:51], v[176:179], v[206:209], v[48:51]
	v_mfma_f32_16x16x32_bf16 v[36:39], v[144:147], v[214:217], v[36:39]
	v_mfma_f32_16x16x32_bf16 v[32:35], v[176:179], v[214:217], v[32:35]
	v_mfma_f32_16x16x32_bf16 v[84:87], v[148:151], v[194:197], v[84:87]
	v_mfma_f32_16x16x32_bf16 v[80:83], v[180:183], v[194:197], v[80:83]
	v_mfma_f32_16x16x32_bf16 v[68:71], v[148:151], v[202:205], v[68:71]
	v_mfma_f32_16x16x32_bf16 v[64:67], v[180:183], v[202:205], v[64:67]
	v_mfma_f32_16x16x32_bf16 v[52:55], v[148:151], v[210:213], v[52:55]
	v_mfma_f32_16x16x32_bf16 v[48:51], v[180:183], v[210:213], v[48:51]
	v_mfma_f32_16x16x32_bf16 v[36:39], v[148:151], v[218:221], v[36:39]
	v_mfma_f32_16x16x32_bf16 v[32:35], v[180:183], v[218:221], v[32:35]
	s_setprio 0
	s_barrier
	s_add_i32 s59, 0, 0x18000
	s_add_i32 s60, 0, 0x1c000
	v_add_u32_e32 v140, s59, v192
	v_add_u32_e32 v152, s60, v192
	ds_read_b128 v[128:131], v140
	ds_read_b128 v[132:135], v140 offset:1024
	ds_read_b128 v[136:139], v140 offset:2048
	ds_read_b128 v[140:143], v140 offset:3072
	ds_read_b128 v[144:147], v152
	ds_read_b128 v[148:151], v152 offset:1024
	ds_read_b128 v[176:179], v152 offset:2048
	ds_read_b128 v[180:183], v152 offset:3072
	s_add_u32 s8, s8, 0x80000
	s_addc_u32 s9, s9, 0
	s_mov_b32 m0, s68
	v_lshl_add_u64 v[228:229], s[8:9], 0, v[164:165]
	ds_read_b128 v[184:187], v193 offset:32768
	ds_read_b128 v[194:197], v193 offset:33792
	ds_read_b128 v[198:201], v193 offset:34816
	ds_read_b128 v[202:205], v193 offset:35840
	ds_read_b128 v[206:209], v193 offset:36864
	ds_read_b128 v[210:213], v193 offset:37888
	ds_read_b128 v[214:217], v193 offset:38912
	ds_read_b128 v[218:221], v193 offset:39936
	global_load_lds_dwordx4 v[228:229], off
	v_lshl_add_u64 v[228:229], s[8:9], 0, v[168:169]
	s_mov_b32 m0, s69
	s_nop 0
	global_load_lds_dwordx4 v[228:229], off
	s_waitcnt vmcnt(8)
	s_waitcnt lgkmcnt(0)
	s_setprio 1
	s_barrier
	v_mfma_f32_16x16x32_bf16 v[28:31], v[128:131], v[184:187], v[28:31]
	v_mfma_f32_16x16x32_bf16 v[24:27], v[136:139], v[184:187], v[24:27]
	v_mfma_f32_16x16x32_bf16 v[12:15], v[128:131], v[198:201], v[12:15]
	v_mfma_f32_16x16x32_bf16 v[8:11], v[136:139], v[198:201], v[8:11]
	v_mfma_f32_16x16x32_bf16 v[124:127], v[128:131], v[206:209], v[124:127]
	v_mfma_f32_16x16x32_bf16 v[120:123], v[136:139], v[206:209], v[120:123]
	v_mfma_f32_16x16x32_bf16 v[108:111], v[128:131], v[214:217], v[108:111]
	v_mfma_f32_16x16x32_bf16 v[104:107], v[136:139], v[214:217], v[104:107]
	v_mfma_f32_16x16x32_bf16 v[28:31], v[132:135], v[194:197], v[28:31]
	v_mfma_f32_16x16x32_bf16 v[24:27], v[140:143], v[194:197], v[24:27]
	v_mfma_f32_16x16x32_bf16 v[12:15], v[132:135], v[202:205], v[12:15]
	v_mfma_f32_16x16x32_bf16 v[8:11], v[140:143], v[202:205], v[8:11]
	v_mfma_f32_16x16x32_bf16 v[124:127], v[132:135], v[210:213], v[124:127]
	v_mfma_f32_16x16x32_bf16 v[120:123], v[140:143], v[210:213], v[120:123]
	v_mfma_f32_16x16x32_bf16 v[108:111], v[132:135], v[218:221], v[108:111]
	v_mfma_f32_16x16x32_bf16 v[104:107], v[140:143], v[218:221], v[104:107]
	s_setprio 0
	s_setprio 1
	v_mfma_f32_16x16x32_bf16 v[20:23], v[144:147], v[184:187], v[20:23]
	v_mfma_f32_16x16x32_bf16 v[16:19], v[176:179], v[184:187], v[16:19]
	v_mfma_f32_16x16x32_bf16 v[4:7], v[144:147], v[198:201], v[4:7]
	v_mfma_f32_16x16x32_bf16 v[0:3], v[176:179], v[198:201], v[0:3]
	v_mfma_f32_16x16x32_bf16 v[116:119], v[144:147], v[206:209], v[116:119]
	v_mfma_f32_16x16x32_bf16 v[112:115], v[176:179], v[206:209], v[112:115]
	v_mfma_f32_16x16x32_bf16 v[100:103], v[144:147], v[214:217], v[100:103]
	v_mfma_f32_16x16x32_bf16 v[96:99], v[176:179], v[214:217], v[96:99]
	v_mfma_f32_16x16x32_bf16 v[20:23], v[148:151], v[194:197], v[20:23]
	v_mfma_f32_16x16x32_bf16 v[16:19], v[180:183], v[194:197], v[16:19]
	v_mfma_f32_16x16x32_bf16 v[4:7], v[148:151], v[202:205], v[4:7]
	v_mfma_f32_16x16x32_bf16 v[0:3], v[180:183], v[202:205], v[0:3]
	v_mfma_f32_16x16x32_bf16 v[116:119], v[148:151], v[210:213], v[116:119]
	v_mfma_f32_16x16x32_bf16 v[112:115], v[180:183], v[210:213], v[112:115]
	v_mfma_f32_16x16x32_bf16 v[100:103], v[148:151], v[218:221], v[100:103]
	v_mfma_f32_16x16x32_bf16 v[96:99], v[180:183], v[218:221], v[96:99]
	s_setprio 0
	s_barrier
; #define PG8_STAGE(bufoff, gbase, voff) do { _Pragma("unroll") for (int _i = 0; _i < 2; ++_i) \
;         __builtin_amdgcn_global_load_lds((const unsigned*)((const char*)(gbase) + (voff)[_i]), (PG8_LAS unsigned*)(lds + (bufoff) + ldsw + _i * 8192), 16, 0, 0); } while (0)
; #define PG8_LDA(dst, b, h) do { _Pragma("unroll") for (int m = 0; m < 4; ++m) _Pragma("unroll") for (int k = 0; k < 2; ++k) dst[m][k] = *(const PG8_LAS bf16x8*)(lds + PG8_SA(b, h) + aoff + m * 2048 + k * 1024); } while (0)
; #define PG8_MMA(ai, bj, At, Bt) do { __builtin_amdgcn_s_setprio(1); _Pragma("unroll") for (int m = 0; m < 4; ++m) _Pragma("unroll") for (int n = 0; n < 2; ++n) _Pragma("unroll") for (int k = 0; k < 2; ++k) \
;         acc[ai][bj][m][n] = __builtin_amdgcn_mfma_f32_16x16x32_bf16(Bt[n][k], At[m][k], acc[ai][bj][m][n], 0, 0, 0); __builtin_amdgcn_s_setprio(0); } while (0)
; #define PG8_WAIT_V(n) asm volatile("s_waitcnt vmcnt(" #n ")" ::: "memory")
; #define PG8_WAIT_L(n) asm volatile("s_waitcnt lgkmcnt(" #n ")" ::: "memory")
; #define PG8_BAR __builtin_amdgcn_s_barrier()
; #define PG8_SCHED __builtin_amdgcn_sched_barrier(0)
; template <class Epi, class Sched, bool ALIGN_EPI = false, bool SP2 = false>
; __device__ __forceinline__ void gemm_phase(PG8_LAS unsigned char* lds, const Gemm g, const Sched& S, const Epi& E) {
;     ...
;             PG8_LDA(At, 1, 1); PG8_STAGE(PG8_SB(1, 0), b3, voffB); PG8_STAGE(PG8_SB(1, 1), b3 + hstep, voffB); PG8_STAGE(PG8_SA(1, 0), a3, voffA);
;             PG8_WAIT_V(8); PG8_WAIT_L(0); PG8_BAR; PG8_MMA(1, 0, At, B0); PG8_MMA(1, 1, At, B1); PG8_BAR; PG8_SCHED;
;     ...
;         if constexpr (ALIGN_EPI) { if (wr == 0) PG8_BAR; }
	s_add_i32 s8, s59, s66
	v_lshl_add_u64 v[188:189], v[188:189], 0, vcc
	s_mov_b32 m0, s8
	ds_read_b128 v[184:187], v193 offset:49152
	ds_read_b128 v[194:197], v193 offset:50176
	ds_read_b128 v[198:201], v193 offset:51200
	ds_read_b128 v[202:205], v193 offset:52224
	ds_read_b128 v[206:209], v193 offset:53248
	ds_read_b128 v[210:213], v193 offset:54272
	ds_read_b128 v[214:217], v193 offset:55296
	ds_read_b128 v[218:221], v193 offset:56320
	global_load_lds_dwordx4 v[188:189], off
	s_add_i32 m0, s8, 0x2000
	s_add_u32 s4, s4, 0x80080
	v_lshl_add_u64 v[188:189], v[222:223], 0, vcc
	s_addc_u32 s5, s5, 0
	s_add_i32 s8, s60, s66
	global_load_lds_dwordx4 v[188:189], off
	v_lshl_add_u64 v[188:189], s[4:5], 0, v[166:167]
	s_mov_b32 m0, s8
	s_nop 0
	global_load_lds_dwordx4 v[188:189], off
	v_lshl_add_u64 v[188:189], s[4:5], 0, v[170:171]
	s_add_i32 m0, s8, 0x2000
	s_nop 0
	global_load_lds_dwordx4 v[188:189], off
	v_lshl_add_u64 v[188:189], v[224:225], 0, vcc
	s_mov_b32 m0, s72
	s_nop 0
	global_load_lds_dwordx4 v[188:189], off
	v_lshl_add_u64 v[188:189], v[226:227], 0, vcc
	s_mov_b32 m0, s73
	s_nop 0
	global_load_lds_dwordx4 v[188:189], off
	s_waitcnt vmcnt(8)
	s_waitcnt lgkmcnt(0)
	s_setprio 1
	s_barrier
	v_mfma_f32_16x16x32_bf16 v[92:95], v[128:131], v[184:187], v[92:95]
	v_mfma_f32_16x16x32_bf16 v[88:91], v[136:139], v[184:187], v[88:91]
	v_mfma_f32_16x16x32_bf16 v[76:79], v[128:131], v[198:201], v[76:79]
	v_mfma_f32_16x16x32_bf16 v[72:75], v[136:139], v[198:201], v[72:75]
	v_mfma_f32_16x16x32_bf16 v[60:63], v[128:131], v[206:209], v[60:63]
	v_mfma_f32_16x16x32_bf16 v[56:59], v[136:139], v[206:209], v[56:59]
	v_mfma_f32_16x16x32_bf16 v[44:47], v[128:131], v[214:217], v[44:47]
	v_mfma_f32_16x16x32_bf16 v[40:43], v[136:139], v[214:217], v[40:43]
	v_mfma_f32_16x16x32_bf16 v[92:95], v[132:135], v[194:197], v[92:95]
	v_mfma_f32_16x16x32_bf16 v[88:91], v[140:143], v[194:197], v[88:91]
	v_mfma_f32_16x16x32_bf16 v[76:79], v[132:135], v[202:205], v[76:79]
	v_mfma_f32_16x16x32_bf16 v[72:75], v[140:143], v[202:205], v[72:75]
	v_mfma_f32_16x16x32_bf16 v[60:63], v[132:135], v[210:213], v[60:63]
	v_mfma_f32_16x16x32_bf16 v[56:59], v[140:143], v[210:213], v[56:59]
	v_mfma_f32_16x16x32_bf16 v[44:47], v[132:135], v[218:221], v[44:47]
	v_mfma_f32_16x16x32_bf16 v[40:43], v[140:143], v[218:221], v[40:43]
	s_setprio 0
	s_setprio 1
	v_mfma_f32_16x16x32_bf16 v[84:87], v[144:147], v[184:187], v[84:87]
	v_mfma_f32_16x16x32_bf16 v[80:83], v[176:179], v[184:187], v[80:83]
	v_mfma_f32_16x16x32_bf16 v[68:71], v[144:147], v[198:201], v[68:71]
	v_mfma_f32_16x16x32_bf16 v[64:67], v[176:179], v[198:201], v[64:67]
	v_mfma_f32_16x16x32_bf16 v[52:55], v[144:147], v[206:209], v[52:55]
	v_mfma_f32_16x16x32_bf16 v[48:51], v[176:179], v[206:209], v[48:51]
	v_mfma_f32_16x16x32_bf16 v[36:39], v[144:147], v[214:217], v[36:39]
	v_mfma_f32_16x16x32_bf16 v[32:35], v[176:179], v[214:217], v[32:35]
	v_mfma_f32_16x16x32_bf16 v[84:87], v[148:151], v[194:197], v[84:87]
	v_mfma_f32_16x16x32_bf16 v[80:83], v[180:183], v[194:197], v[80:83]
	v_mfma_f32_16x16x32_bf16 v[68:71], v[148:151], v[202:205], v[68:71]
	v_mfma_f32_16x16x32_bf16 v[64:67], v[180:183], v[202:205], v[64:67]
	v_mfma_f32_16x16x32_bf16 v[52:55], v[148:151], v[210:213], v[52:55]
	v_mfma_f32_16x16x32_bf16 v[48:51], v[180:183], v[210:213], v[48:51]
	v_mfma_f32_16x16x32_bf16 v[36:39], v[148:151], v[218:221], v[36:39]
	v_mfma_f32_16x16x32_bf16 v[32:35], v[180:183], v[218:221], v[32:35]
	s_setprio 0
	s_barrier
	s_add_i32 s58, s58, 2
	s_add_u32 s0, s0, 0x100
	s_addc_u32 s1, s1, 0
	s_add_u32 s56, s56, 0x100
	s_addc_u32 s57, s57, 0
	s_cmp_gt_u32 s58, 29
	s_cbranch_scc0 .LBB0_447
	s_and_b64 vcc, exec, s[40:41]
	s_cbranch_vccz .LBB0_450
	s_barrier

; #define PG8_STAGE(bufoff, gbase, voff) do { _Pragma("unroll") for (int _i = 0; _i < 2; ++_i) \
;         __builtin_amdgcn_global_load_lds((const unsigned*)((const char*)(gbase) + (voff)[_i]), (PG8_LAS unsigned*)(lds + (bufoff) + ldsw + _i * 8192), 16, 0, 0); } while (0)
; #define PG8_WAIT_V(n) asm volatile("s_waitcnt vmcnt(" #n ")" ::: "memory")
; #define PG8_BAR __builtin_amdgcn_s_barrier()
; template <class Epi, class Sched, bool ALIGN_EPI = false, bool SP2 = false>
; __device__ __forceinline__ void gemm_phase(PG8_LAS unsigned char* lds, const Gemm g, const Sched& S, const Epi& E) {
;     ...
; #pragma unroll
;     for (int a = 0; a < 2; ++a)
; #pragma unroll
;         for (int b = 0; b < 2; ++b)
; #pragma unroll
;             for (int m = 0; m < 4; ++m)
; #pragma unroll
;                 for (int n = 0; n < 2; ++n) acc[a][b][m][n] = (f32x4){0.f, 0.f, 0.f, 0.f};
;     ...
;         PG8_WAIT_V(2); PG8_BAR;
;         PG8_STAGE(PG8_SB(1, 0), cB + kstep, voffB); PG8_STAGE(PG8_SA(1, 0), cA + kstep, voffA); PG8_STAGE(PG8_SB(1, 1), cB + hstep + kstep, voffB);
;         PG8_WAIT_V(6); PG8_BAR;
.LBB0_873:
	v_lshl_add_u64 v[6:7], s[24:25], 0, v[152:153]
	v_mov_b32_e32 v33, v153
	v_lshl_add_u64 v[8:9], s[24:25], 0, v[32:33]
	v_mov_b32_e32 v41, v153
	s_and_b32 s34, s5, 3
	s_add_i32 m0, s35, 0x18000
	v_lshl_add_u64 v[6:7], v[6:7], 0, s[74:75]
	v_lshl_add_u64 v[10:11], s[14:15], 0, v[40:41]
	v_mov_b32_e32 v35, v153
	s_lshl_b32 s36, s4, 6
	s_lshl_b32 s4, s4, 13
	s_lshl_b32 s5, s34, 12
	s_waitcnt vmcnt(2)
	s_barrier
	global_load_lds_dwordx4 v[6:7], off
	v_lshl_add_u64 v[6:7], v[8:9], 0, s[74:75]
	s_add_i32 m0, s35, 0x1a000
	s_add_i32 s40, s35, 0x8000
	s_add_i32 s41, s35, 0xa000
	v_lshl_add_u64 v[12:13], s[14:15], 0, v[34:35]
	global_load_lds_dwordx4 v[6:7], off
	v_lshl_add_u64 v[6:7], v[10:11], 0, s[74:75]
	s_mov_b32 m0, s40
	s_add_u32 s0, s24, 0x80080
	global_load_lds_dwordx4 v[6:7], off
	v_lshl_add_u64 v[6:7], v[12:13], 0, s[74:75]
	s_mov_b32 m0, s41
	s_addc_u32 s1, s25, 0
	global_load_lds_dwordx4 v[6:7], off
	s_add_i32 m0, s35, 0x1c000
	v_lshl_add_u64 v[6:7], s[0:1], 0, v[152:153]
	global_load_lds_dwordx4 v[6:7], off
	v_lshl_add_u64 v[6:7], s[0:1], 0, v[32:33]
	s_add_i32 m0, s35, 0x1e000
	v_and_b32_e32 v144, 15, v220
	global_load_lds_dwordx4 v[6:7], off
	v_and_b32_e32 v6, 48, v220
	v_lshlrev_b32_e32 v7, 2, v220
	v_lshl_or_b32 v6, v144, 6, v6
	v_and_b32_e32 v7, 32, v7
	v_bitop3_b32 v8, v6, s4, v7 bitop3:0xde
	v_bitop3_b32 v50, v6, s5, v7 bitop3:0xde
	v_lshlrev_b32_e32 v6, 15, v4
	v_and_b32_e32 v6, 0xffff0000, v6
	v_lshl_add_u32 v3, v3, 12, v6
	v_and_b32_e32 v4, 1, v4
	v_lshl_or_b32 v3, v4, 6, v3
	v_lshl_add_u32 v42, v5, 1, v3
	v_lshlrev_b32_e32 v3, 15, v0
	v_and_b32_e32 v3, 0xffff0000, v3
	v_lshl_add_u32 v1, v1, 12, v3
	v_and_b32_e32 v0, 1, v0
	v_lshl_or_b32 v0, v0, 6, v1
	s_waitcnt vmcnt(6)
	v_lshl_add_u32 v44, v2, 1, v0
	v_mov_b32_e32 v2, v153
	v_mov_b32_e32 v3, v153
	v_readlane_b32 s0, v253, 27
	v_mov_b32_e32 v0, v153
	v_mov_b32_e32 v1, v153
	v_add_u32_e32 v51, 0, v8
	v_mov_b64_e32 v[6:7], v[2:3]
	v_mov_b64_e32 v[18:19], v[2:3]
	v_mov_b64_e32 v[22:23], v[2:3]
	v_mov_b64_e32 v[38:39], v[2:3]
	v_mov_b64_e32 v[54:55], v[2:3]
	v_mov_b64_e32 v[66:67], v[2:3]
	v_mov_b64_e32 v[70:71], v[2:3]
	v_mov_b64_e32 v[10:11], v[2:3]
	v_mov_b64_e32 v[14:15], v[2:3]
	v_mov_b64_e32 v[26:27], v[2:3]
	v_mov_b64_e32 v[30:31], v[2:3]
	v_mov_b64_e32 v[58:59], v[2:3]
	v_mov_b64_e32 v[62:63], v[2:3]
	v_mov_b64_e32 v[74:75], v[2:3]
	v_mov_b64_e32 v[78:79], v[2:3]
	v_mov_b64_e32 v[82:83], v[2:3]
	v_mov_b64_e32 v[86:87], v[2:3]
	v_mov_b64_e32 v[98:99], v[2:3]
	v_mov_b64_e32 v[102:103], v[2:3]
	v_mov_b64_e32 v[114:115], v[2:3]
	v_mov_b64_e32 v[118:119], v[2:3]
	v_mov_b64_e32 v[130:131], v[2:3]
	v_mov_b64_e32 v[134:135], v[2:3]
	v_mov_b64_e32 v[90:91], v[2:3]
	v_mov_b64_e32 v[94:95], v[2:3]
	v_mov_b64_e32 v[106:107], v[2:3]
	v_mov_b64_e32 v[110:111], v[2:3]
	v_mov_b64_e32 v[122:123], v[2:3]
	v_mov_b64_e32 v[126:127], v[2:3]
	v_mov_b64_e32 v[138:139], v[2:3]
	v_mov_b64_e32 v[142:143], v[2:3]
	s_mov_b32 s12, s0
	v_readlane_b32 s0, v253, 39
	v_mov_b32_e32 v43, v153
	v_mov_b32_e32 v45, v153
	s_mov_b32 s43, 0
	v_mov_b64_e32 v[4:5], v[0:1]
	v_mov_b64_e32 v[16:17], v[0:1]
	v_mov_b64_e32 v[20:21], v[0:1]
	v_mov_b64_e32 v[36:37], v[0:1]
	v_mov_b64_e32 v[52:53], v[0:1]
	v_mov_b64_e32 v[64:65], v[0:1]
	v_mov_b64_e32 v[68:69], v[0:1]
	v_mov_b64_e32 v[8:9], v[0:1]
	v_mov_b64_e32 v[12:13], v[0:1]
	v_mov_b64_e32 v[24:25], v[0:1]
	v_mov_b64_e32 v[28:29], v[0:1]
	v_mov_b64_e32 v[56:57], v[0:1]
	v_mov_b64_e32 v[60:61], v[0:1]
	v_mov_b64_e32 v[72:73], v[0:1]
	v_mov_b64_e32 v[76:77], v[0:1]
	v_mov_b64_e32 v[80:81], v[0:1]
	v_mov_b64_e32 v[84:85], v[0:1]
	v_mov_b64_e32 v[96:97], v[0:1]
	v_mov_b64_e32 v[100:101], v[0:1]
	v_mov_b64_e32 v[112:113], v[0:1]
	v_mov_b64_e32 v[116:117], v[0:1]
	v_mov_b64_e32 v[128:129], v[0:1]
	v_mov_b64_e32 v[132:133], v[0:1]
	v_mov_b64_e32 v[88:89], v[0:1]
	v_mov_b64_e32 v[92:93], v[0:1]
	v_mov_b64_e32 v[104:105], v[0:1]
	v_mov_b64_e32 v[108:109], v[0:1]
	v_mov_b64_e32 v[120:121], v[0:1]
	v_mov_b64_e32 v[124:125], v[0:1]
	v_mov_b64_e32 v[136:137], v[0:1]
	v_mov_b64_e32 v[140:141], v[0:1]
	s_mov_b32 s42, s0
	s_barrier
	v_readlane_b32 s1, v253, 40
	s_branch .LBB0_876
	s_nop 0
	s_nop 0
	s_nop 0
	s_nop 0

; #define PG8_STAGE(bufoff, gbase, voff) do { _Pragma("unroll") for (int _i = 0; _i < 2; ++_i) \
;         __builtin_amdgcn_global_load_lds((const unsigned*)((const char*)(gbase) + (voff)[_i]), (PG8_LAS unsigned*)(lds + (bufoff) + ldsw + _i * 8192), 16, 0, 0); } while (0)
; #define PG8_LDA(dst, b, h) do { _Pragma("unroll") for (int m = 0; m < 4; ++m) _Pragma("unroll") for (int k = 0; k < 2; ++k) dst[m][k] = *(const PG8_LAS bf16x8*)(lds + PG8_SA(b, h) + aoff + m * 2048 + k * 1024); } while (0)
; #define PG8_LDB(dst, b, h) do { _Pragma("unroll") for (int n = 0; n < 2; ++n) _Pragma("unroll") for (int k = 0; k < 2; ++k) dst[n][k] = *(const PG8_LAS bf16x8*)(lds + PG8_SB(b, h) + boff + n * 2048 + k * 1024); } while (0)
; #define PG8_MMA(ai, bj, At, Bt) do { __builtin_amdgcn_s_setprio(1); _Pragma("unroll") for (int m = 0; m < 4; ++m) _Pragma("unroll") for (int n = 0; n < 2; ++n) _Pragma("unroll") for (int k = 0; k < 2; ++k) \
;         acc[ai][bj][m][n] = __builtin_amdgcn_mfma_f32_16x16x32_bf16(Bt[n][k], At[m][k], acc[ai][bj][m][n], 0, 0, 0); __builtin_amdgcn_s_setprio(0); } while (0)
; #define PG8_WAIT_V(n) asm volatile("s_waitcnt vmcnt(" #n ")" ::: "memory")
; #define PG8_WAIT_L(n) asm volatile("s_waitcnt lgkmcnt(" #n ")" ::: "memory")
; #define PG8_BAR __builtin_amdgcn_s_barrier()
; #define PG8_SCHED __builtin_amdgcn_sched_barrier(0)
; template <class Epi, class Sched, bool ALIGN_EPI = false, bool SP2 = false>
; __device__ __forceinline__ void gemm_phase(PG8_LAS unsigned char* lds, const Gemm g, const Sched& S, const Epi& E) {
;     ...
;             PG8_LDB(B0, 0, 0); PG8_LDB(B1, 0, 1); PG8_SCHED; PG8_LDA(At, 0, 0); PG8_STAGE(PG8_SA(1, 1), a1 + hstep, voffA);
;             PG8_WAIT_V(8); PG8_WAIT_L(0); PG8_BAR; PG8_MMA(0, 0, At, B0); PG8_MMA(0, 1, At, B1); PG8_BAR; PG8_SCHED;
;             PG8_LDA(At, 0, 1); PG8_STAGE(PG8_SB(0, 0), b2, voffB); PG8_STAGE(PG8_SB(0, 1), b2 + hstep, voffB); PG8_STAGE(PG8_SA(0, 0), a2, voffA);
.LBB0_883:
	s_add_u32 s26, s14, s24
	s_addc_u32 s27, s15, s25
	s_add_u32 s26, s26, 0x100
	s_addc_u32 s27, s27, 0
	s_add_u32 s50, s45, s24
	s_addc_u32 s51, s46, s25
	s_add_i32 s52, 0, 0x10000
	s_cmpk_eq_i32 s24, 0xf00
	s_cselect_b32 s29, s19, s27
	s_cselect_b32 s28, s47, s26
	v_add_u32_e32 v145, s52, v50
	s_cselect_b32 s27, s17, s51
	s_cselect_b32 s26, s48, s50
	s_add_i32 s53, 0, 0x14000
	ds_read_b128 v[146:149], v145
	ds_read_b128 v[164:167], v145 offset:1024
	ds_read_b128 v[168:171], v145 offset:2048
	ds_read_b128 v[172:175], v145 offset:3072
	v_add_u32_e32 v145, s53, v50
	ds_read_b128 v[176:179], v145
	ds_read_b128 v[180:183], v145 offset:1024
	ds_read_b128 v[184:187], v145 offset:2048
	ds_read_b128 v[188:191], v145 offset:3072
	v_lshl_add_u64 v[150:151], v[46:47], 0, s[24:25]
	s_add_i32 m0, s35, 0xc000
	ds_read_b128 v[192:195], v51
	ds_read_b128 v[196:199], v51 offset:1024
	ds_read_b128 v[200:203], v51 offset:2048
	ds_read_b128 v[204:207], v51 offset:3072
	ds_read_b128 v[208:211], v51 offset:4096
	ds_read_b128 v[212:215], v51 offset:5120
	ds_read_b128 v[216:219], v51 offset:6144
	ds_read_b128 v[222:225], v51 offset:7168
	global_load_lds_dwordx4 v[150:151], off
	v_lshl_add_u64 v[150:151], v[48:49], 0, s[24:25]
	s_add_i32 m0, s35, 0xe000
	s_nop 0
	global_load_lds_dwordx4 v[150:151], off
	s_waitcnt vmcnt(8)
	s_waitcnt lgkmcnt(0)
	s_setprio 1
	s_barrier
	v_mfma_f32_16x16x32_bf16 v[140:143], v[146:149], v[192:195], v[140:143]
	v_mfma_f32_16x16x32_bf16 v[136:139], v[168:171], v[192:195], v[136:139]
	v_mfma_f32_16x16x32_bf16 v[124:127], v[146:149], v[200:203], v[124:127]
	v_mfma_f32_16x16x32_bf16 v[120:123], v[168:171], v[200:203], v[120:123]
	v_mfma_f32_16x16x32_bf16 v[108:111], v[146:149], v[208:211], v[108:111]
	v_mfma_f32_16x16x32_bf16 v[104:107], v[168:171], v[208:211], v[104:107]
	v_mfma_f32_16x16x32_bf16 v[92:95], v[146:149], v[216:219], v[92:95]
	v_mfma_f32_16x16x32_bf16 v[88:91], v[168:171], v[216:219], v[88:91]
	v_mfma_f32_16x16x32_bf16 v[140:143], v[164:167], v[196:199], v[140:143]
	v_mfma_f32_16x16x32_bf16 v[136:139], v[172:175], v[196:199], v[136:139]
	v_mfma_f32_16x16x32_bf16 v[124:127], v[164:167], v[204:207], v[124:127]
	v_mfma_f32_16x16x32_bf16 v[120:123], v[172:175], v[204:207], v[120:123]
	v_mfma_f32_16x16x32_bf16 v[108:111], v[164:167], v[212:215], v[108:111]
	v_mfma_f32_16x16x32_bf16 v[104:107], v[172:175], v[212:215], v[104:107]
	v_mfma_f32_16x16x32_bf16 v[92:95], v[164:167], v[222:225], v[92:95]
	v_mfma_f32_16x16x32_bf16 v[88:91], v[172:175], v[222:225], v[88:91]
	s_setprio 0
	s_setprio 1
	v_mfma_f32_16x16x32_bf16 v[132:135], v[176:179], v[192:195], v[132:135]
	v_mfma_f32_16x16x32_bf16 v[128:131], v[184:187], v[192:195], v[128:131]
	v_mfma_f32_16x16x32_bf16 v[116:119], v[176:179], v[200:203], v[116:119]
	v_mfma_f32_16x16x32_bf16 v[112:115], v[184:187], v[200:203], v[112:115]
	v_mfma_f32_16x16x32_bf16 v[100:103], v[176:179], v[208:211], v[100:103]
	v_mfma_f32_16x16x32_bf16 v[96:99], v[184:187], v[208:211], v[96:99]
	v_mfma_f32_16x16x32_bf16 v[84:87], v[176:179], v[216:219], v[84:87]
	v_mfma_f32_16x16x32_bf16 v[80:83], v[184:187], v[216:219], v[80:83]
	v_mfma_f32_16x16x32_bf16 v[132:135], v[180:183], v[196:199], v[132:135]
	v_mfma_f32_16x16x32_bf16 v[128:131], v[188:191], v[196:199], v[128:131]
	v_mfma_f32_16x16x32_bf16 v[116:119], v[180:183], v[204:207], v[116:119]
	v_mfma_f32_16x16x32_bf16 v[112:115], v[188:191], v[204:207], v[112:115]
	v_mfma_f32_16x16x32_bf16 v[100:103], v[180:183], v[212:215], v[100:103]
	v_mfma_f32_16x16x32_bf16 v[96:99], v[188:191], v[212:215], v[96:99]
	v_mfma_f32_16x16x32_bf16 v[84:87], v[180:183], v[222:225], v[84:87]
	v_mfma_f32_16x16x32_bf16 v[80:83], v[188:191], v[222:225], v[80:83]
	s_setprio 0
	s_barrier
	s_add_i32 s50, s52, s33
	v_lshl_add_u64 v[150:151], s[26:27], 0, v[152:153]
	s_mov_b32 m0, s50
	ds_read_b128 v[192:195], v51 offset:16384
	ds_read_b128 v[196:199], v51 offset:17408
	ds_read_b128 v[200:203], v51 offset:18432
	ds_read_b128 v[204:207], v51 offset:19456
	ds_read_b128 v[208:211], v51 offset:20480
	ds_read_b128 v[212:215], v51 offset:21504
	ds_read_b128 v[216:219], v51 offset:22528
	ds_read_b128 v[222:225], v51 offset:23552
	global_load_lds_dwordx4 v[150:151], off
	s_add_i32 m0, s50, 0x2000
	s_add_u32 s50, s26, 0x80000
	v_lshl_add_u64 v[226:227], s[26:27], 0, v[32:33]
	s_addc_u32 s51, s27, 0
	s_add_i32 s52, s53, s33
	global_load_lds_dwordx4 v[226:227], off
	v_lshl_add_u64 v[228:229], s[50:51], 0, v[152:153]
	s_mov_b32 m0, s52
	v_lshl_add_u64 v[230:231], s[28:29], 0, v[34:35]
	global_load_lds_dwordx4 v[228:229], off
	v_lshl_add_u64 v[228:229], s[50:51], 0, v[32:33]
	s_add_i32 m0, s52, 0x2000
	s_nop 0
	global_load_lds_dwordx4 v[228:229], off
	v_lshl_add_u64 v[228:229], s[28:29], 0, v[40:41]
	s_mov_b32 m0, s35
	s_nop 0
	global_load_lds_dwordx4 v[228:229], off
	s_mov_b32 m0, s37
	s_nop 0
	global_load_lds_dwordx4 v[230:231], off
	s_waitcnt vmcnt(8)
	s_waitcnt lgkmcnt(0)
	s_setprio 1
	s_barrier
; #define PG8_STAGE(bufoff, gbase, voff) do { _Pragma("unroll") for (int _i = 0; _i < 2; ++_i) \
;         __builtin_amdgcn_global_load_lds((const unsigned*)((const char*)(gbase) + (voff)[_i]), (PG8_LAS unsigned*)(lds + (bufoff) + ldsw + _i * 8192), 16, 0, 0); } while (0)
; #define PG8_LDA(dst, b, h) do { _Pragma("unroll") for (int m = 0; m < 4; ++m) _Pragma("unroll") for (int k = 0; k < 2; ++k) dst[m][k] = *(const PG8_LAS bf16x8*)(lds + PG8_SA(b, h) + aoff + m * 2048 + k * 1024); } while (0)
; #define PG8_LDB(dst, b, h) do { _Pragma("unroll") for (int n = 0; n < 2; ++n) _Pragma("unroll") for (int k = 0; k < 2; ++k) dst[n][k] = *(const PG8_LAS bf16x8*)(lds + PG8_SB(b, h) + boff + n * 2048 + k * 1024); } while (0)
; #define PG8_MMA(ai, bj, At, Bt) do { __builtin_amdgcn_s_setprio(1); _Pragma("unroll") for (int m = 0; m < 4; ++m) _Pragma("unroll") for (int n = 0; n < 2; ++n) _Pragma("unroll") for (int k = 0; k < 2; ++k) \
;         acc[ai][bj][m][n] = __builtin_amdgcn_mfma_f32_16x16x32_bf16(Bt[n][k], At[m][k], acc[ai][bj][m][n], 0, 0, 0); __builtin_amdgcn_s_setprio(0); } while (0)
; #define PG8_WAIT_V(n) asm volatile("s_waitcnt vmcnt(" #n ")" ::: "memory")
; #define PG8_WAIT_L(n) asm volatile("s_waitcnt lgkmcnt(" #n ")" ::: "memory")
; #define PG8_BAR __builtin_amdgcn_s_barrier()
; #define PG8_SCHED __builtin_amdgcn_sched_barrier(0)
; template <class Epi, class Sched, bool ALIGN_EPI = false, bool SP2 = false>
; __device__ __forceinline__ void gemm_phase(PG8_LAS unsigned char* lds, const Gemm g, const Sched& S, const Epi& E) {
;     ...
;             PG8_WAIT_V(8); PG8_WAIT_L(0); PG8_BAR; PG8_MMA(1, 0, At, B0); PG8_MMA(1, 1, At, B1); PG8_BAR; PG8_SCHED;
;             PG8_LDB(B0, 1, 0); PG8_LDB(B1, 1, 1); PG8_SCHED; PG8_LDA(At, 1, 0); PG8_STAGE(PG8_SA(0, 1), a2 + hstep, voffA);
;             PG8_WAIT_V(8); PG8_WAIT_L(0); PG8_BAR; PG8_MMA(0, 0, At, B0); PG8_MMA(0, 1, At, B1); PG8_BAR; PG8_SCHED;
	v_mfma_f32_16x16x32_bf16 v[76:79], v[146:149], v[192:195], v[76:79]
	v_mfma_f32_16x16x32_bf16 v[72:75], v[168:171], v[192:195], v[72:75]
	v_mfma_f32_16x16x32_bf16 v[60:63], v[146:149], v[200:203], v[60:63]
	v_mfma_f32_16x16x32_bf16 v[56:59], v[168:171], v[200:203], v[56:59]
	v_mfma_f32_16x16x32_bf16 v[28:31], v[146:149], v[208:211], v[28:31]
	v_mfma_f32_16x16x32_bf16 v[24:27], v[168:171], v[208:211], v[24:27]
	v_mfma_f32_16x16x32_bf16 v[12:15], v[146:149], v[216:219], v[12:15]
	v_mfma_f32_16x16x32_bf16 v[8:11], v[168:171], v[216:219], v[8:11]
	v_mfma_f32_16x16x32_bf16 v[76:79], v[164:167], v[196:199], v[76:79]
	v_mfma_f32_16x16x32_bf16 v[72:75], v[172:175], v[196:199], v[72:75]
	v_mfma_f32_16x16x32_bf16 v[60:63], v[164:167], v[204:207], v[60:63]
	v_mfma_f32_16x16x32_bf16 v[56:59], v[172:175], v[204:207], v[56:59]
	v_mfma_f32_16x16x32_bf16 v[28:31], v[164:167], v[212:215], v[28:31]
	v_mfma_f32_16x16x32_bf16 v[24:27], v[172:175], v[212:215], v[24:27]
	v_mfma_f32_16x16x32_bf16 v[12:15], v[164:167], v[222:225], v[12:15]
	v_mfma_f32_16x16x32_bf16 v[8:11], v[172:175], v[222:225], v[8:11]
	s_setprio 0
	s_setprio 1
	v_mfma_f32_16x16x32_bf16 v[68:71], v[176:179], v[192:195], v[68:71]
	v_mfma_f32_16x16x32_bf16 v[64:67], v[184:187], v[192:195], v[64:67]
	v_mfma_f32_16x16x32_bf16 v[52:55], v[176:179], v[200:203], v[52:55]
	v_mfma_f32_16x16x32_bf16 v[36:39], v[184:187], v[200:203], v[36:39]
	v_mfma_f32_16x16x32_bf16 v[20:23], v[176:179], v[208:211], v[20:23]
	v_mfma_f32_16x16x32_bf16 v[16:19], v[184:187], v[208:211], v[16:19]
	v_mfma_f32_16x16x32_bf16 v[4:7], v[176:179], v[216:219], v[4:7]
	v_mfma_f32_16x16x32_bf16 v[0:3], v[184:187], v[216:219], v[0:3]
	v_mfma_f32_16x16x32_bf16 v[68:71], v[180:183], v[196:199], v[68:71]
	v_mfma_f32_16x16x32_bf16 v[64:67], v[188:191], v[196:199], v[64:67]
	v_mfma_f32_16x16x32_bf16 v[52:55], v[180:183], v[204:207], v[52:55]
	v_mfma_f32_16x16x32_bf16 v[36:39], v[188:191], v[204:207], v[36:39]
	v_mfma_f32_16x16x32_bf16 v[20:23], v[180:183], v[212:215], v[20:23]
	v_mfma_f32_16x16x32_bf16 v[16:19], v[188:191], v[212:215], v[16:19]
	v_mfma_f32_16x16x32_bf16 v[4:7], v[180:183], v[222:225], v[4:7]
	v_mfma_f32_16x16x32_bf16 v[0:3], v[188:191], v[222:225], v[0:3]
	s_setprio 0
	s_barrier
	s_add_i32 s50, 0, 0x18000
	v_add_u32_e32 v145, s50, v50
	s_add_i32 s51, 0, 0x1c000
	ds_read_b128 v[146:149], v145
	ds_read_b128 v[164:167], v145 offset:1024
	ds_read_b128 v[168:171], v145 offset:2048
	ds_read_b128 v[172:175], v145 offset:3072
	v_add_u32_e32 v145, s51, v50
	ds_read_b128 v[176:179], v145
	ds_read_b128 v[180:183], v145 offset:1024
	ds_read_b128 v[184:187], v145 offset:2048
	ds_read_b128 v[188:191], v145 offset:3072
	s_add_u32 s28, s28, 0x80000
	s_addc_u32 s29, s29, 0
	s_mov_b32 m0, s38
	v_lshl_add_u64 v[232:233], s[28:29], 0, v[40:41]
	ds_read_b128 v[192:195], v51 offset:32768
	ds_read_b128 v[196:199], v51 offset:33792
	ds_read_b128 v[200:203], v51 offset:34816
	ds_read_b128 v[204:207], v51 offset:35840
	ds_read_b128 v[208:211], v51 offset:36864
	ds_read_b128 v[212:215], v51 offset:37888
	ds_read_b128 v[216:219], v51 offset:38912
	ds_read_b128 v[222:225], v51 offset:39936
	global_load_lds_dwordx4 v[232:233], off
	v_lshl_add_u64 v[232:233], s[28:29], 0, v[34:35]
	s_mov_b32 m0, s39
	s_nop 0
	global_load_lds_dwordx4 v[232:233], off
	s_waitcnt vmcnt(8)
	s_waitcnt lgkmcnt(0)
	s_setprio 1
	s_barrier
	v_mfma_f32_16x16x32_bf16 v[140:143], v[146:149], v[192:195], v[140:143]
	v_mfma_f32_16x16x32_bf16 v[136:139], v[168:171], v[192:195], v[136:139]
	v_mfma_f32_16x16x32_bf16 v[124:127], v[146:149], v[200:203], v[124:127]
	v_mfma_f32_16x16x32_bf16 v[120:123], v[168:171], v[200:203], v[120:123]
	v_mfma_f32_16x16x32_bf16 v[108:111], v[146:149], v[208:211], v[108:111]
	v_mfma_f32_16x16x32_bf16 v[104:107], v[168:171], v[208:211], v[104:107]
	v_mfma_f32_16x16x32_bf16 v[92:95], v[146:149], v[216:219], v[92:95]
	v_mfma_f32_16x16x32_bf16 v[88:91], v[168:171], v[216:219], v[88:91]
	v_mfma_f32_16x16x32_bf16 v[140:143], v[164:167], v[196:199], v[140:143]
	v_mfma_f32_16x16x32_bf16 v[136:139], v[172:175], v[196:199], v[136:139]
	v_mfma_f32_16x16x32_bf16 v[124:127], v[164:167], v[204:207], v[124:127]
	v_mfma_f32_16x16x32_bf16 v[120:123], v[172:175], v[204:207], v[120:123]
	v_mfma_f32_16x16x32_bf16 v[108:111], v[164:167], v[212:215], v[108:111]
	v_mfma_f32_16x16x32_bf16 v[104:107], v[172:175], v[212:215], v[104:107]
	v_mfma_f32_16x16x32_bf16 v[92:95], v[164:167], v[222:225], v[92:95]
	v_mfma_f32_16x16x32_bf16 v[88:91], v[172:175], v[222:225], v[88:91]
	s_setprio 0
	s_setprio 1
	v_mfma_f32_16x16x32_bf16 v[132:135], v[176:179], v[192:195], v[132:135]
	v_mfma_f32_16x16x32_bf16 v[128:131], v[184:187], v[192:195], v[128:131]
	v_mfma_f32_16x16x32_bf16 v[116:119], v[176:179], v[200:203], v[116:119]
	v_mfma_f32_16x16x32_bf16 v[112:115], v[184:187], v[200:203], v[112:115]
	v_mfma_f32_16x16x32_bf16 v[100:103], v[176:179], v[208:211], v[100:103]
	v_mfma_f32_16x16x32_bf16 v[96:99], v[184:187], v[208:211], v[96:99]
	v_mfma_f32_16x16x32_bf16 v[84:87], v[176:179], v[216:219], v[84:87]
	v_mfma_f32_16x16x32_bf16 v[80:83], v[184:187], v[216:219], v[80:83]
	v_mfma_f32_16x16x32_bf16 v[132:135], v[180:183], v[196:199], v[132:135]
	v_mfma_f32_16x16x32_bf16 v[128:131], v[188:191], v[196:199], v[128:131]
	v_mfma_f32_16x16x32_bf16 v[116:119], v[180:183], v[204:207], v[116:119]
	v_mfma_f32_16x16x32_bf16 v[112:115], v[188:191], v[204:207], v[112:115]
	v_mfma_f32_16x16x32_bf16 v[100:103], v[180:183], v[212:215], v[100:103]
	v_mfma_f32_16x16x32_bf16 v[96:99], v[188:191], v[212:215], v[96:99]
	v_mfma_f32_16x16x32_bf16 v[84:87], v[180:183], v[222:225], v[84:87]
	v_mfma_f32_16x16x32_bf16 v[80:83], v[188:191], v[222:225], v[80:83]
	s_setprio 0
	s_barrier
; #define PG8_STAGE(bufoff, gbase, voff) do { _Pragma("unroll") for (int _i = 0; _i < 2; ++_i) \
;         __builtin_amdgcn_global_load_lds((const unsigned*)((const char*)(gbase) + (voff)[_i]), (PG8_LAS unsigned*)(lds + (bufoff) + ldsw + _i * 8192), 16, 0, 0); } while (0)
; #define PG8_LDA(dst, b, h) do { _Pragma("unroll") for (int m = 0; m < 4; ++m) _Pragma("unroll") for (int k = 0; k < 2; ++k) dst[m][k] = *(const PG8_LAS bf16x8*)(lds + PG8_SA(b, h) + aoff + m * 2048 + k * 1024); } while (0)
; #define PG8_MMA(ai, bj, At, Bt) do { __builtin_amdgcn_s_setprio(1); _Pragma("unroll") for (int m = 0; m < 4; ++m) _Pragma("unroll") for (int n = 0; n < 2; ++n) _Pragma("unroll") for (int k = 0; k < 2; ++k) \
;         acc[ai][bj][m][n] = __builtin_amdgcn_mfma_f32_16x16x32_bf16(Bt[n][k], At[m][k], acc[ai][bj][m][n], 0, 0, 0); __builtin_amdgcn_s_setprio(0); } while (0)
; #define PG8_WAIT_V(n) asm volatile("s_waitcnt vmcnt(" #n ")" ::: "memory")
; #define PG8_WAIT_L(n) asm volatile("s_waitcnt lgkmcnt(" #n ")" ::: "memory")
; #define PG8_BAR __builtin_amdgcn_s_barrier()
; #define PG8_SCHED __builtin_amdgcn_sched_barrier(0)
; template <class Epi, class Sched, bool ALIGN_EPI = false, bool SP2 = false>
; __device__ __forceinline__ void gemm_phase(PG8_LAS unsigned char* lds, const Gemm g, const Sched& S, const Epi& E) {
;     ...
;             PG8_LDA(At, 1, 1); PG8_STAGE(PG8_SB(1, 0), b3, voffB); PG8_STAGE(PG8_SB(1, 1), b3 + hstep, voffB); PG8_STAGE(PG8_SA(1, 0), a3, voffA);
;             PG8_WAIT_V(8); PG8_WAIT_L(0); PG8_BAR; PG8_MMA(1, 0, At, B0); PG8_MMA(1, 1, At, B1); PG8_BAR; PG8_SCHED;
;     ...
; #pragma unroll
;         for (int a = 0; a < 2; ++a)
; #pragma unroll
;             for (int b = 0; b < 2; ++b)
; #pragma unroll
;                 for (int m = 0; m < 4; ++m)
; #pragma unroll
;                     for (int n = 0; n < 2; ++n) acc[a][b][m][n] = (f32x4){0.f, 0.f, 0.f, 0.f};
;         cur = nxt; cA = nA; cB = nB; ++ui;
	s_add_i32 s28, s50, s33
	v_lshl_add_u64 v[150:151], v[150:151], 0, s[74:75]
	s_mov_b32 m0, s28
	ds_read_b128 v[192:195], v51 offset:49152
	ds_read_b128 v[196:199], v51 offset:50176
	ds_read_b128 v[200:203], v51 offset:51200
	ds_read_b128 v[204:207], v51 offset:52224
	ds_read_b128 v[208:211], v51 offset:53248
	ds_read_b128 v[212:215], v51 offset:54272
	ds_read_b128 v[216:219], v51 offset:55296
	ds_read_b128 v[222:225], v51 offset:56320
	global_load_lds_dwordx4 v[150:151], off
	s_add_i32 m0, s28, 0x2000
	s_add_u32 s26, s26, 0x80080
	v_lshl_add_u64 v[150:151], v[226:227], 0, s[74:75]
	s_addc_u32 s27, s27, 0
	s_add_i32 s28, s51, s33
	global_load_lds_dwordx4 v[150:151], off
	v_lshl_add_u64 v[150:151], s[26:27], 0, v[152:153]
	s_mov_b32 m0, s28
	s_nop 0
	global_load_lds_dwordx4 v[150:151], off
	v_lshl_add_u64 v[150:151], s[26:27], 0, v[32:33]
	s_add_i32 m0, s28, 0x2000
	s_nop 0
	global_load_lds_dwordx4 v[150:151], off
	v_lshl_add_u64 v[150:151], v[228:229], 0, s[74:75]
	s_mov_b32 m0, s40
	s_nop 0
	global_load_lds_dwordx4 v[150:151], off
	v_lshl_add_u64 v[150:151], v[230:231], 0, s[74:75]
	s_mov_b32 m0, s41
	s_nop 0
	global_load_lds_dwordx4 v[150:151], off
	s_waitcnt vmcnt(8)
	s_waitcnt lgkmcnt(0)
	s_setprio 1
	s_barrier
	v_mfma_f32_16x16x32_bf16 v[76:79], v[146:149], v[192:195], v[76:79]
	v_mfma_f32_16x16x32_bf16 v[72:75], v[168:171], v[192:195], v[72:75]
	v_mfma_f32_16x16x32_bf16 v[60:63], v[146:149], v[200:203], v[60:63]
	v_mfma_f32_16x16x32_bf16 v[56:59], v[168:171], v[200:203], v[56:59]
	v_mfma_f32_16x16x32_bf16 v[28:31], v[146:149], v[208:211], v[28:31]
	v_mfma_f32_16x16x32_bf16 v[24:27], v[168:171], v[208:211], v[24:27]
	v_mfma_f32_16x16x32_bf16 v[12:15], v[146:149], v[216:219], v[12:15]
	v_mfma_f32_16x16x32_bf16 v[8:11], v[168:171], v[216:219], v[8:11]
	v_mfma_f32_16x16x32_bf16 v[76:79], v[164:167], v[196:199], v[76:79]
	v_mfma_f32_16x16x32_bf16 v[72:75], v[172:175], v[196:199], v[72:75]
	v_mfma_f32_16x16x32_bf16 v[60:63], v[164:167], v[204:207], v[60:63]
	v_mfma_f32_16x16x32_bf16 v[56:59], v[172:175], v[204:207], v[56:59]
	v_mfma_f32_16x16x32_bf16 v[28:31], v[164:167], v[212:215], v[28:31]
	v_mfma_f32_16x16x32_bf16 v[24:27], v[172:175], v[212:215], v[24:27]
	v_mfma_f32_16x16x32_bf16 v[12:15], v[164:167], v[222:225], v[12:15]
	v_mfma_f32_16x16x32_bf16 v[8:11], v[172:175], v[222:225], v[8:11]
	s_setprio 0
	s_setprio 1
	v_mfma_f32_16x16x32_bf16 v[68:71], v[176:179], v[192:195], v[68:71]
	v_mfma_f32_16x16x32_bf16 v[64:67], v[184:187], v[192:195], v[64:67]
	v_mfma_f32_16x16x32_bf16 v[52:55], v[176:179], v[200:203], v[52:55]
	v_mfma_f32_16x16x32_bf16 v[36:39], v[184:187], v[200:203], v[36:39]
	v_mfma_f32_16x16x32_bf16 v[20:23], v[176:179], v[208:211], v[20:23]
	v_mfma_f32_16x16x32_bf16 v[16:19], v[184:187], v[208:211], v[16:19]
	v_mfma_f32_16x16x32_bf16 v[4:7], v[176:179], v[216:219], v[4:7]
	v_mfma_f32_16x16x32_bf16 v[0:3], v[184:187], v[216:219], v[0:3]
	v_mfma_f32_16x16x32_bf16 v[68:71], v[180:183], v[196:199], v[68:71]
	v_mfma_f32_16x16x32_bf16 v[64:67], v[188:191], v[196:199], v[64:67]
	v_mfma_f32_16x16x32_bf16 v[52:55], v[180:183], v[204:207], v[52:55]
	v_mfma_f32_16x16x32_bf16 v[36:39], v[188:191], v[204:207], v[36:39]
	v_mfma_f32_16x16x32_bf16 v[20:23], v[180:183], v[212:215], v[20:23]
	v_mfma_f32_16x16x32_bf16 v[16:19], v[188:191], v[212:215], v[16:19]
	v_mfma_f32_16x16x32_bf16 v[4:7], v[180:183], v[222:225], v[4:7]
	v_mfma_f32_16x16x32_bf16 v[0:3], v[188:191], v[222:225], v[0:3]
	s_setprio 0
	s_barrier
	s_add_i32 s49, s49, 2
	s_add_u32 s24, s24, 0x100
	s_addc_u32 s25, s25, 0
	s_cmp_gt_u32 s49, 29
	s_cbranch_scc0 .LBB0_883
	s_add_u32 s24, s45, 0xffffff00
	s_addc_u32 s25, s46, -1
	s_andn2_b64 vcc, exec, s[4:5]
	s_cbranch_vccnz .LBB0_874
	v_mov_b32_e32 v0, 0
	s_mov_b32 s12, s16
	s_mov_b32 s42, s18
	s_mov_b64 s[14:15], s[22:23]
	s_mov_b32 s43, s44
	v_mov_b32_e32 v1, v0
	v_mov_b32_e32 v2, v0
	v_mov_b32_e32 v3, v0
	v_mov_b32_e32 v4, v0
	v_mov_b32_e32 v5, v0
	v_mov_b32_e32 v6, v0
	v_mov_b32_e32 v7, v0
	v_mov_b32_e32 v16, v0
	v_mov_b32_e32 v17, v0
	v_mov_b32_e32 v18, v0
	v_mov_b32_e32 v19, v0
	v_mov_b32_e32 v20, v0
	v_mov_b32_e32 v21, v0
	v_mov_b32_e32 v22, v0
	v_mov_b32_e32 v23, v0
	v_mov_b32_e32 v36, v0
	v_mov_b32_e32 v37, v0
	v_mov_b32_e32 v38, v0
	v_mov_b32_e32 v39, v0
	v_mov_b32_e32 v52, v0
	v_mov_b32_e32 v53, v0
	v_mov_b32_e32 v54, v0
	v_mov_b32_e32 v55, v0
	v_mov_b32_e32 v64, v0
	v_mov_b32_e32 v65, v0
	v_mov_b32_e32 v66, v0
	v_mov_b32_e32 v67, v0
	v_mov_b32_e32 v68, v0
	v_mov_b32_e32 v69, v0
	v_mov_b32_e32 v70, v0
	v_mov_b32_e32 v71, v0
	v_mov_b32_e32 v8, v0
	v_mov_b32_e32 v9, v0
	v_mov_b32_e32 v10, v0
	v_mov_b32_e32 v11, v0
	v_mov_b32_e32 v12, v0
	v_mov_b32_e32 v13, v0
	v_mov_b32_e32 v14, v0
	v_mov_b32_e32 v15, v0
	v_mov_b32_e32 v24, v0
	v_mov_b32_e32 v25, v0
	v_mov_b32_e32 v26, v0
	v_mov_b32_e32 v27, v0
	v_mov_b32_e32 v28, v0
	v_mov_b32_e32 v29, v0
	v_mov_b32_e32 v30, v0
	v_mov_b32_e32 v31, v0
	v_mov_b32_e32 v56, v0
	v_mov_b32_e32 v57, v0
	v_mov_b32_e32 v58, v0
	v_mov_b32_e32 v59, v0
	v_mov_b32_e32 v60, v0
	v_mov_b32_e32 v61, v0
	v_mov_b32_e32 v62, v0
	v_mov_b32_e32 v63, v0
	v_mov_b32_e32 v72, v0
	v_mov_b32_e32 v73, v0
	v_mov_b32_e32 v74, v0
	v_mov_b32_e32 v75, v0
	v_mov_b32_e32 v76, v0
	v_mov_b32_e32 v77, v0
	v_mov_b32_e32 v78, v0
	v_mov_b32_e32 v79, v0
	v_mov_b32_e32 v80, v0
	v_mov_b32_e32 v81, v0
	v_mov_b32_e32 v82, v0
	v_mov_b32_e32 v83, v0
	v_mov_b32_e32 v84, v0
	v_mov_b32_e32 v85, v0
	v_mov_b32_e32 v86, v0
	v_mov_b32_e32 v87, v0
	v_mov_b32_e32 v96, v0
	v_mov_b32_e32 v97, v0
	v_mov_b32_e32 v98, v0
	v_mov_b32_e32 v99, v0
	v_mov_b32_e32 v100, v0
	v_mov_b32_e32 v101, v0
	v_mov_b32_e32 v102, v0
	v_mov_b32_e32 v103, v0
	v_mov_b32_e32 v112, v0
	v_mov_b32_e32 v113, v0
	v_mov_b32_e32 v114, v0
	v_mov_b32_e32 v115, v0
	v_mov_b32_e32 v116, v0
	v_mov_b32_e32 v117, v0
	v_mov_b32_e32 v118, v0
	v_mov_b32_e32 v119, v0
	v_mov_b32_e32 v128, v0
	v_mov_b32_e32 v129, v0
	v_mov_b32_e32 v130, v0
	v_mov_b32_e32 v131, v0
	v_mov_b32_e32 v132, v0
	v_mov_b32_e32 v133, v0
	v_mov_b32_e32 v134, v0
	v_mov_b32_e32 v135, v0
	v_mov_b32_e32 v88, v0
	v_mov_b32_e32 v89, v0
	v_mov_b32_e32 v90, v0
	v_mov_b32_e32 v91, v0
	v_mov_b32_e32 v92, v0
	v_mov_b32_e32 v93, v0
	v_mov_b32_e32 v94, v0
	v_mov_b32_e32 v95, v0
	v_mov_b32_e32 v104, v0
	v_mov_b32_e32 v105, v0
	v_mov_b32_e32 v106, v0
	v_mov_b32_e32 v107, v0
	v_mov_b32_e32 v108, v0
	v_mov_b32_e32 v109, v0
	v_mov_b32_e32 v110, v0
	v_mov_b32_e32 v111, v0
	v_mov_b32_e32 v120, v0
	v_mov_b32_e32 v121, v0
	v_mov_b32_e32 v122, v0
	v_mov_b32_e32 v123, v0
	v_mov_b32_e32 v124, v0
	v_mov_b32_e32 v125, v0
	v_mov_b32_e32 v126, v0
	v_mov_b32_e32 v127, v0
	v_mov_b32_e32 v136, v0
	v_mov_b32_e32 v137, v0
	v_mov_b32_e32 v138, v0
	v_mov_b32_e32 v139, v0
	v_mov_b32_e32 v140, v0
	v_mov_b32_e32 v141, v0
	v_mov_b32_e32 v142, v0
	v_mov_b32_e32 v143, v0
	s_andn2_b64 vcc, exec, s[0:1]
	s_cbranch_vccnz .LBB0_875

; #define PG8_STAGE(bufoff, gbase, voff) do { _Pragma("unroll") for (int _i = 0; _i < 2; ++_i) \
;         __builtin_amdgcn_global_load_lds((const unsigned*)((const char*)(gbase) + (voff)[_i]), (PG8_LAS unsigned*)(lds + (bufoff) + ldsw + _i * 8192), 16, 0, 0); } while (0)
; #define PG8_WAIT_V(n) asm volatile("s_waitcnt vmcnt(" #n ")" ::: "memory")
; #define PG8_BAR __builtin_amdgcn_s_barrier()
; template <class Epi, class Sched, bool ALIGN_EPI = false, bool SP2 = false>
; __device__ __forceinline__ void gemm_phase(PG8_LAS unsigned char* lds, const Gemm g, const Sched& S, const Epi& E) {
;     ...
;     const int aoff = lds_byte(wr * 64 + fr, fq * 8), boff = lds_byte(wc * 32 + fr, fq * 8);
;     ...
;         PG8_WAIT_V(2); PG8_BAR;
;         PG8_STAGE(PG8_SB(1, 0), cB + kstep, voffB); PG8_STAGE(PG8_SA(1, 0), cA + kstep, voffA); PG8_STAGE(PG8_SB(1, 1), cB + hstep + kstep, voffB);
;         PG8_WAIT_V(6); PG8_BAR;
.LBB0_1048:
	s_lshl_b32 s1, s1, 5
	s_and_b32 s41, s1, 0x60
	s_lshl_b32 s40, s4, 6
	s_lshl_b32 s18, s4, 13
	s_lshl_b32 s1, s41, 7
	s_add_u32 s4, s8, 0x26100000
	s_addc_u32 s5, s9, 0
	s_add_i32 m0, s36, 0x18000
	v_lshl_add_u64 v[6:7], v[6:7], 0, s[74:75]
	s_waitcnt vmcnt(2)
	s_barrier
	global_load_lds_dwordx4 v[6:7], off
	v_lshl_add_u64 v[4:5], v[4:5], 0, s[74:75]
	s_add_i32 m0, s36, 0x1a000
	s_add_i32 s42, s36, 0x8000
	s_add_i32 s43, s36, 0xa000
	global_load_lds_dwordx4 v[4:5], off
	v_lshl_add_u64 v[0:1], v[0:1], 0, s[74:75]
	s_mov_b32 m0, s42
	s_add_u32 s16, s28, 0x80080
	global_load_lds_dwordx4 v[0:1], off
	v_lshl_add_u64 v[0:1], v[2:3], 0, s[74:75]
	s_mov_b32 m0, s43
	s_addc_u32 s17, s29, 0
	global_load_lds_dwordx4 v[0:1], off
	s_add_i32 m0, s36, 0x1c000
	v_lshl_add_u64 v[0:1], s[16:17], 0, v[152:153]
	global_load_lds_dwordx4 v[0:1], off
	v_lshl_add_u64 v[0:1], s[16:17], 0, v[128:129]
	s_add_i32 m0, s36, 0x1e000
	v_bfe_u32 v143, v8, 4, 2
	global_load_lds_dwordx4 v[0:1], off
	v_and_b32_e32 v142, 15, v8
	v_lshlrev_b32_e32 v0, 4, v143
	v_lshlrev_b32_e32 v1, 2, v8
	v_lshl_or_b32 v0, v142, 6, v0
	v_and_b32_e32 v1, 32, v1
	v_bitop3_b32 v2, v0, s18, v1 bitop3:0xde
	v_bitop3_b32 v144, v0, s1, v1 bitop3:0xde
	v_lshlrev_b32_e32 v0, 15, v13
	v_and_b32_e32 v0, 0xffff0000, v0
	v_lshl_add_u32 v0, v12, 12, v0
	v_and_b32_e32 v1, 1, v13
	v_lshl_or_b32 v0, v1, 6, v0
	v_lshl_add_u32 v134, v14, 1, v0
	v_lshlrev_b32_e32 v0, 15, v9
	v_and_b32_e32 v0, 0xffff0000, v0
	s_waitcnt vmcnt(6)
	v_lshl_add_u32 v0, v10, 12, v0
	v_and_b32_e32 v1, 1, v9
	s_cmpk_lt_u32 s0, 0x100
	v_lshl_or_b32 v0, v1, 6, v0
	v_readlane_b32 s0, v253, 33
	s_cselect_b64 s[16:17], -1, 0
	v_mov_b32_e32 v135, v153
	v_lshl_add_u32 v136, v11, 1, v0
	v_mov_b32_e32 v137, v153
	s_mov_b32 s44, 0
	v_add_u32_e32 v145, 0, v2
	v_readlane_b32 s45, v253, 32
	s_mov_b32 s46, s0
	s_barrier
	v_readlane_b32 s1, v253, 34
	s_branch .LBB0_1051
	s_nop 0
	s_nop 0
	s_nop 0
	s_nop 0

; #define PG8_STAGE(bufoff, gbase, voff) do { _Pragma("unroll") for (int _i = 0; _i < 2; ++_i) \
;         __builtin_amdgcn_global_load_lds((const unsigned*)((const char*)(gbase) + (voff)[_i]), (PG8_LAS unsigned*)(lds + (bufoff) + ldsw + _i * 8192), 16, 0, 0); } while (0)
; #define PG8_LDA(dst, b, h) do { _Pragma("unroll") for (int m = 0; m < 4; ++m) _Pragma("unroll") for (int k = 0; k < 2; ++k) dst[m][k] = *(const PG8_LAS bf16x8*)(lds + PG8_SA(b, h) + aoff + m * 2048 + k * 1024); } while (0)
; #define PG8_LDB(dst, b, h) do { _Pragma("unroll") for (int n = 0; n < 2; ++n) _Pragma("unroll") for (int k = 0; k < 2; ++k) dst[n][k] = *(const PG8_LAS bf16x8*)(lds + PG8_SB(b, h) + boff + n * 2048 + k * 1024); } while (0)
; #define PG8_MMA(ai, bj, At, Bt) do { __builtin_amdgcn_s_setprio(1); _Pragma("unroll") for (int m = 0; m < 4; ++m) _Pragma("unroll") for (int n = 0; n < 2; ++n) _Pragma("unroll") for (int k = 0; k < 2; ++k) \
;         acc[ai][bj][m][n] = __builtin_amdgcn_mfma_f32_16x16x32_bf16(Bt[n][k], At[m][k], acc[ai][bj][m][n], 0, 0, 0); __builtin_amdgcn_s_setprio(0); } while (0)
; #define PG8_WAIT_V(n) asm volatile("s_waitcnt vmcnt(" #n ")" ::: "memory")
; #define PG8_BAR __builtin_amdgcn_s_barrier()
; template <class Epi, class Sched, bool ALIGN_EPI = false, bool SP2 = false>
; __device__ __forceinline__ void gemm_phase(PG8_LAS unsigned char* lds, const Gemm g, const Sched& S, const Epi& E) {
;     ...
;         for (int t = 0; t < nt; t += 2) {
;             const bool last = (t == nt - 2);
;             const char* a1 = cA + (size_t)(t + 1) * kstep;
;             const char* a2 = last ? nA : cA + (size_t)(t + 2) * kstep; const char* b2 = last ? nB : cB + (size_t)(t + 2) * kstep;
;             const char* a3 = a2 + kstep; const char* b3 = b2 + kstep;
;             if (last && has_next) S.a_ready(nxt);
;             if constexpr (SP2) {
;             PG8_LDB(B0, 0, 0); PG8_LDB(B1, 0, 1); PG8_SCHED; PG8_LDA(At, 0, 0); PG8_STAGE(PG8_SA(1, 1), a1 + hstep, voffA);
;             PG8_WAIT_V(8); PG8_WAIT_L(0); PG8_BAR; PG8_MMA(0, 0, At, B0); PG8_MMA(0, 1, At, B1); PG8_BAR; PG8_SCHED;
;             PG8_LDA(At, 0, 1); PG8_STAGE(PG8_SB(0, 0), b2, voffB); PG8_STAGE(PG8_SB(0, 1), b2 + hstep, voffB); PG8_STAGE(PG8_SA(0, 0), a2, voffA);
;             PG8_WAIT_V(8); PG8_WAIT_L(0); PG8_BAR; PG8_MMA(1, 0, At, B0); PG8_MMA(1, 1, At, B1); PG8_BAR; PG8_SCHED;
.LBB0_1058:
	s_add_u32 s28, s26, 0xfff80080
	s_addc_u32 s29, s27, -1
	s_add_i32 s52, 0, 0x10000
	s_cmp_eq_u32 s51, 28
	s_cselect_b32 s31, s21, s29
	s_cselect_b32 s30, s47, s28
	v_add_u32_e32 v150, s52, v144
	s_cselect_b32 s29, s19, s50
	s_cselect_b32 s28, s48, s49
	s_add_i32 s54, 0, 0x14000
	ds_read_b128 v[138:141], v150
	ds_read_b128 v[146:149], v150 offset:1024
	ds_read_b128 v[164:167], v150 offset:2048
	ds_read_b128 v[168:171], v150 offset:3072
	v_add_u32_e32 v150, s54, v144
	ds_read_b128 v[172:175], v150
	ds_read_b128 v[176:179], v150 offset:1024
	ds_read_b128 v[180:183], v150 offset:2048
	ds_read_b128 v[184:187], v150 offset:3072
	v_lshl_add_u64 v[150:151], s[26:27], 0, v[134:135]
	s_add_i32 m0, s36, 0xc000
	ds_read_b128 v[188:191], v145
	ds_read_b128 v[192:195], v145 offset:1024
	ds_read_b128 v[196:199], v145 offset:2048
	ds_read_b128 v[200:203], v145 offset:3072
	ds_read_b128 v[204:207], v145 offset:4096
	ds_read_b128 v[208:211], v145 offset:5120
	ds_read_b128 v[212:215], v145 offset:6144
	ds_read_b128 v[216:219], v145 offset:7168
	global_load_lds_dwordx4 v[150:151], off
	v_lshl_add_u64 v[150:151], s[26:27], 0, v[136:137]
	s_add_i32 m0, s36, 0xe000
	s_nop 0
	global_load_lds_dwordx4 v[150:151], off
	s_waitcnt vmcnt(8)
	s_waitcnt lgkmcnt(0)
	s_setprio 1
	s_barrier
	v_mfma_f32_16x16x32_bf16 v[124:127], v[138:141], v[188:191], v[124:127]
	v_mfma_f32_16x16x32_bf16 v[120:123], v[164:167], v[188:191], v[120:123]
	v_mfma_f32_16x16x32_bf16 v[108:111], v[138:141], v[196:199], v[108:111]
	v_mfma_f32_16x16x32_bf16 v[104:107], v[164:167], v[196:199], v[104:107]
	v_mfma_f32_16x16x32_bf16 v[92:95], v[138:141], v[204:207], v[92:95]
	v_mfma_f32_16x16x32_bf16 v[88:91], v[164:167], v[204:207], v[88:91]
	v_mfma_f32_16x16x32_bf16 v[76:79], v[138:141], v[212:215], v[76:79]
	v_mfma_f32_16x16x32_bf16 v[72:75], v[164:167], v[212:215], v[72:75]
	v_mfma_f32_16x16x32_bf16 v[124:127], v[146:149], v[192:195], v[124:127]
	v_mfma_f32_16x16x32_bf16 v[120:123], v[168:171], v[192:195], v[120:123]
	v_mfma_f32_16x16x32_bf16 v[108:111], v[146:149], v[200:203], v[108:111]
	v_mfma_f32_16x16x32_bf16 v[104:107], v[168:171], v[200:203], v[104:107]
	v_mfma_f32_16x16x32_bf16 v[92:95], v[146:149], v[208:211], v[92:95]
	v_mfma_f32_16x16x32_bf16 v[88:91], v[168:171], v[208:211], v[88:91]
	v_mfma_f32_16x16x32_bf16 v[76:79], v[146:149], v[216:219], v[76:79]
	v_mfma_f32_16x16x32_bf16 v[72:75], v[168:171], v[216:219], v[72:75]
	s_setprio 0
	s_setprio 1
	v_mfma_f32_16x16x32_bf16 v[116:119], v[172:175], v[188:191], v[116:119]
	v_mfma_f32_16x16x32_bf16 v[112:115], v[180:183], v[188:191], v[112:115]
	v_mfma_f32_16x16x32_bf16 v[100:103], v[172:175], v[196:199], v[100:103]
	v_mfma_f32_16x16x32_bf16 v[96:99], v[180:183], v[196:199], v[96:99]
	v_mfma_f32_16x16x32_bf16 v[84:87], v[172:175], v[204:207], v[84:87]
	v_mfma_f32_16x16x32_bf16 v[80:83], v[180:183], v[204:207], v[80:83]
	v_mfma_f32_16x16x32_bf16 v[68:71], v[172:175], v[212:215], v[68:71]
	v_mfma_f32_16x16x32_bf16 v[64:67], v[180:183], v[212:215], v[64:67]
	v_mfma_f32_16x16x32_bf16 v[116:119], v[176:179], v[192:195], v[116:119]
	v_mfma_f32_16x16x32_bf16 v[112:115], v[184:187], v[192:195], v[112:115]
	v_mfma_f32_16x16x32_bf16 v[100:103], v[176:179], v[200:203], v[100:103]
	v_mfma_f32_16x16x32_bf16 v[96:99], v[184:187], v[200:203], v[96:99]
	v_mfma_f32_16x16x32_bf16 v[84:87], v[176:179], v[208:211], v[84:87]
	v_mfma_f32_16x16x32_bf16 v[80:83], v[184:187], v[208:211], v[80:83]
	v_mfma_f32_16x16x32_bf16 v[68:71], v[176:179], v[216:219], v[68:71]
	v_mfma_f32_16x16x32_bf16 v[64:67], v[184:187], v[216:219], v[64:67]
	s_setprio 0
	s_barrier
	s_add_i32 s52, s52, s35
	v_lshl_add_u64 v[150:151], s[28:29], 0, v[152:153]
	s_mov_b32 m0, s52
	ds_read_b128 v[188:191], v145 offset:16384
	ds_read_b128 v[192:195], v145 offset:17408
	ds_read_b128 v[196:199], v145 offset:18432
	ds_read_b128 v[200:203], v145 offset:19456
	ds_read_b128 v[204:207], v145 offset:20480
	ds_read_b128 v[208:211], v145 offset:21504
	ds_read_b128 v[212:215], v145 offset:22528
	ds_read_b128 v[216:219], v145 offset:23552
	global_load_lds_dwordx4 v[150:151], off
	s_add_i32 m0, s52, 0x2000
	s_add_u32 s52, s28, 0x80000
	v_lshl_add_u64 v[220:221], s[28:29], 0, v[128:129]
	s_addc_u32 s53, s29, 0
	s_add_i32 s54, s54, s35
	global_load_lds_dwordx4 v[220:221], off
	v_lshl_add_u64 v[222:223], s[52:53], 0, v[152:153]
	s_mov_b32 m0, s54
	v_lshl_add_u64 v[224:225], s[30:31], 0, v[130:131]
	global_load_lds_dwordx4 v[222:223], off
	v_lshl_add_u64 v[222:223], s[52:53], 0, v[128:129]
	s_add_i32 m0, s54, 0x2000
	s_nop 0
	global_load_lds_dwordx4 v[222:223], off
	v_lshl_add_u64 v[222:223], s[30:31], 0, v[132:133]
	s_mov_b32 m0, s36
	s_nop 0
	global_load_lds_dwordx4 v[222:223], off
	s_mov_b32 m0, s37
	s_nop 0
	global_load_lds_dwordx4 v[224:225], off
	s_waitcnt vmcnt(8)
	s_waitcnt lgkmcnt(0)
	s_setprio 1
	s_barrier
; #define PG8_STAGE(bufoff, gbase, voff) do { _Pragma("unroll") for (int _i = 0; _i < 2; ++_i) \
;         __builtin_amdgcn_global_load_lds((const unsigned*)((const char*)(gbase) + (voff)[_i]), (PG8_LAS unsigned*)(lds + (bufoff) + ldsw + _i * 8192), 16, 0, 0); } while (0)
; #define PG8_LDA(dst, b, h) do { _Pragma("unroll") for (int m = 0; m < 4; ++m) _Pragma("unroll") for (int k = 0; k < 2; ++k) dst[m][k] = *(const PG8_LAS bf16x8*)(lds + PG8_SA(b, h) + aoff + m * 2048 + k * 1024); } while (0)
; #define PG8_LDB(dst, b, h) do { _Pragma("unroll") for (int n = 0; n < 2; ++n) _Pragma("unroll") for (int k = 0; k < 2; ++k) dst[n][k] = *(const PG8_LAS bf16x8*)(lds + PG8_SB(b, h) + boff + n * 2048 + k * 1024); } while (0)
; #define PG8_MMA(ai, bj, At, Bt) do { __builtin_amdgcn_s_setprio(1); _Pragma("unroll") for (int m = 0; m < 4; ++m) _Pragma("unroll") for (int n = 0; n < 2; ++n) _Pragma("unroll") for (int k = 0; k < 2; ++k) \
;         acc[ai][bj][m][n] = __builtin_amdgcn_mfma_f32_16x16x32_bf16(Bt[n][k], At[m][k], acc[ai][bj][m][n], 0, 0, 0); __builtin_amdgcn_s_setprio(0); } while (0)
; #define PG8_WAIT_V(n) asm volatile("s_waitcnt vmcnt(" #n ")" ::: "memory")
; #define PG8_WAIT_L(n) asm volatile("s_waitcnt lgkmcnt(" #n ")" ::: "memory")
; #define PG8_BAR __builtin_amdgcn_s_barrier()
; #define PG8_SCHED __builtin_amdgcn_sched_barrier(0)
; template <class Epi, class Sched, bool ALIGN_EPI = false, bool SP2 = false>
; __device__ __forceinline__ void gemm_phase(PG8_LAS unsigned char* lds, const Gemm g, const Sched& S, const Epi& E) {
;     ...
;             PG8_WAIT_V(8); PG8_WAIT_L(0); PG8_BAR; PG8_MMA(1, 0, At, B0); PG8_MMA(1, 1, At, B1); PG8_BAR; PG8_SCHED;
;             PG8_LDB(B0, 1, 0); PG8_LDB(B1, 1, 1); PG8_SCHED; PG8_LDA(At, 1, 0); PG8_STAGE(PG8_SA(0, 1), a2 + hstep, voffA);
;             PG8_WAIT_V(8); PG8_WAIT_L(0); PG8_BAR; PG8_MMA(0, 0, At, B0); PG8_MMA(0, 1, At, B1); PG8_BAR; PG8_SCHED;
	v_mfma_f32_16x16x32_bf16 v[60:63], v[138:141], v[188:191], v[60:63]
	v_mfma_f32_16x16x32_bf16 v[56:59], v[164:167], v[188:191], v[56:59]
	v_mfma_f32_16x16x32_bf16 v[44:47], v[138:141], v[196:199], v[44:47]
	v_mfma_f32_16x16x32_bf16 v[40:43], v[164:167], v[196:199], v[40:43]
	v_mfma_f32_16x16x32_bf16 v[28:31], v[138:141], v[204:207], v[28:31]
	v_mfma_f32_16x16x32_bf16 v[24:27], v[164:167], v[204:207], v[24:27]
	v_mfma_f32_16x16x32_bf16 v[12:15], v[138:141], v[212:215], v[12:15]
	v_mfma_f32_16x16x32_bf16 v[8:11], v[164:167], v[212:215], v[8:11]
	v_mfma_f32_16x16x32_bf16 v[60:63], v[146:149], v[192:195], v[60:63]
	v_mfma_f32_16x16x32_bf16 v[56:59], v[168:171], v[192:195], v[56:59]
	v_mfma_f32_16x16x32_bf16 v[44:47], v[146:149], v[200:203], v[44:47]
	v_mfma_f32_16x16x32_bf16 v[40:43], v[168:171], v[200:203], v[40:43]
	v_mfma_f32_16x16x32_bf16 v[28:31], v[146:149], v[208:211], v[28:31]
	v_mfma_f32_16x16x32_bf16 v[24:27], v[168:171], v[208:211], v[24:27]
	v_mfma_f32_16x16x32_bf16 v[12:15], v[146:149], v[216:219], v[12:15]
	v_mfma_f32_16x16x32_bf16 v[8:11], v[168:171], v[216:219], v[8:11]
	s_setprio 0
	s_setprio 1
	v_mfma_f32_16x16x32_bf16 v[52:55], v[172:175], v[188:191], v[52:55]
	v_mfma_f32_16x16x32_bf16 v[48:51], v[180:183], v[188:191], v[48:51]
	v_mfma_f32_16x16x32_bf16 v[36:39], v[172:175], v[196:199], v[36:39]
	v_mfma_f32_16x16x32_bf16 v[32:35], v[180:183], v[196:199], v[32:35]
	v_mfma_f32_16x16x32_bf16 v[20:23], v[172:175], v[204:207], v[20:23]
	v_mfma_f32_16x16x32_bf16 v[16:19], v[180:183], v[204:207], v[16:19]
	v_mfma_f32_16x16x32_bf16 v[4:7], v[172:175], v[212:215], v[4:7]
	v_mfma_f32_16x16x32_bf16 v[0:3], v[180:183], v[212:215], v[0:3]
	v_mfma_f32_16x16x32_bf16 v[52:55], v[176:179], v[192:195], v[52:55]
	v_mfma_f32_16x16x32_bf16 v[48:51], v[184:187], v[192:195], v[48:51]
	v_mfma_f32_16x16x32_bf16 v[36:39], v[176:179], v[200:203], v[36:39]
	v_mfma_f32_16x16x32_bf16 v[32:35], v[184:187], v[200:203], v[32:35]
	v_mfma_f32_16x16x32_bf16 v[20:23], v[176:179], v[208:211], v[20:23]
	v_mfma_f32_16x16x32_bf16 v[16:19], v[184:187], v[208:211], v[16:19]
	v_mfma_f32_16x16x32_bf16 v[4:7], v[176:179], v[216:219], v[4:7]
	v_mfma_f32_16x16x32_bf16 v[0:3], v[184:187], v[216:219], v[0:3]
	s_setprio 0
	s_barrier
	s_add_i32 s52, 0, 0x18000
	s_add_i32 s53, 0, 0x1c000
	v_add_u32_e32 v168, s52, v144
	v_add_u32_e32 v184, s53, v144
	ds_read_b128 v[138:141], v168
	ds_read_b128 v[146:149], v168 offset:1024
	ds_read_b128 v[164:167], v168 offset:2048
	ds_read_b128 v[168:171], v168 offset:3072
	ds_read_b128 v[172:175], v184
	ds_read_b128 v[176:179], v184 offset:1024
	ds_read_b128 v[180:183], v184 offset:2048
	ds_read_b128 v[184:187], v184 offset:3072
	s_add_u32 s30, s30, 0x80000
	s_addc_u32 s31, s31, 0
	s_mov_b32 m0, s38
	v_lshl_add_u64 v[226:227], s[30:31], 0, v[132:133]
	ds_read_b128 v[188:191], v145 offset:32768
	ds_read_b128 v[192:195], v145 offset:33792
	ds_read_b128 v[196:199], v145 offset:34816
	ds_read_b128 v[200:203], v145 offset:35840
	ds_read_b128 v[204:207], v145 offset:36864
	ds_read_b128 v[208:211], v145 offset:37888
	ds_read_b128 v[212:215], v145 offset:38912
	ds_read_b128 v[216:219], v145 offset:39936
	global_load_lds_dwordx4 v[226:227], off
	v_lshl_add_u64 v[226:227], s[30:31], 0, v[130:131]
	s_mov_b32 m0, s39
	s_nop 0
	global_load_lds_dwordx4 v[226:227], off
	s_waitcnt vmcnt(8)
	s_waitcnt lgkmcnt(0)
	s_setprio 1
	s_barrier
	v_mfma_f32_16x16x32_bf16 v[124:127], v[138:141], v[188:191], v[124:127]
	v_mfma_f32_16x16x32_bf16 v[120:123], v[164:167], v[188:191], v[120:123]
	v_mfma_f32_16x16x32_bf16 v[108:111], v[138:141], v[196:199], v[108:111]
	v_mfma_f32_16x16x32_bf16 v[104:107], v[164:167], v[196:199], v[104:107]
	v_mfma_f32_16x16x32_bf16 v[92:95], v[138:141], v[204:207], v[92:95]
	v_mfma_f32_16x16x32_bf16 v[88:91], v[164:167], v[204:207], v[88:91]
	v_mfma_f32_16x16x32_bf16 v[76:79], v[138:141], v[212:215], v[76:79]
	v_mfma_f32_16x16x32_bf16 v[72:75], v[164:167], v[212:215], v[72:75]
	v_mfma_f32_16x16x32_bf16 v[124:127], v[146:149], v[192:195], v[124:127]
	v_mfma_f32_16x16x32_bf16 v[120:123], v[168:171], v[192:195], v[120:123]
	v_mfma_f32_16x16x32_bf16 v[108:111], v[146:149], v[200:203], v[108:111]
	v_mfma_f32_16x16x32_bf16 v[104:107], v[168:171], v[200:203], v[104:107]
	v_mfma_f32_16x16x32_bf16 v[92:95], v[146:149], v[208:211], v[92:95]
	v_mfma_f32_16x16x32_bf16 v[88:91], v[168:171], v[208:211], v[88:91]
	v_mfma_f32_16x16x32_bf16 v[76:79], v[146:149], v[216:219], v[76:79]
	v_mfma_f32_16x16x32_bf16 v[72:75], v[168:171], v[216:219], v[72:75]
	s_setprio 0
	s_setprio 1
	v_mfma_f32_16x16x32_bf16 v[116:119], v[172:175], v[188:191], v[116:119]
	v_mfma_f32_16x16x32_bf16 v[112:115], v[180:183], v[188:191], v[112:115]
	v_mfma_f32_16x16x32_bf16 v[100:103], v[172:175], v[196:199], v[100:103]
	v_mfma_f32_16x16x32_bf16 v[96:99], v[180:183], v[196:199], v[96:99]
	v_mfma_f32_16x16x32_bf16 v[84:87], v[172:175], v[204:207], v[84:87]
	v_mfma_f32_16x16x32_bf16 v[80:83], v[180:183], v[204:207], v[80:83]
	v_mfma_f32_16x16x32_bf16 v[68:71], v[172:175], v[212:215], v[68:71]
	v_mfma_f32_16x16x32_bf16 v[64:67], v[180:183], v[212:215], v[64:67]
	v_mfma_f32_16x16x32_bf16 v[116:119], v[176:179], v[192:195], v[116:119]
	v_mfma_f32_16x16x32_bf16 v[112:115], v[184:187], v[192:195], v[112:115]
	v_mfma_f32_16x16x32_bf16 v[100:103], v[176:179], v[200:203], v[100:103]
	v_mfma_f32_16x16x32_bf16 v[96:99], v[184:187], v[200:203], v[96:99]
	v_mfma_f32_16x16x32_bf16 v[84:87], v[176:179], v[208:211], v[84:87]
	v_mfma_f32_16x16x32_bf16 v[80:83], v[184:187], v[208:211], v[80:83]
	v_mfma_f32_16x16x32_bf16 v[68:71], v[176:179], v[216:219], v[68:71]
	v_mfma_f32_16x16x32_bf16 v[64:67], v[184:187], v[216:219], v[64:67]
	s_setprio 0
	s_barrier
; #define PG8_STAGE(bufoff, gbase, voff) do { _Pragma("unroll") for (int _i = 0; _i < 2; ++_i) \
;         __builtin_amdgcn_global_load_lds((const unsigned*)((const char*)(gbase) + (voff)[_i]), (PG8_LAS unsigned*)(lds + (bufoff) + ldsw + _i * 8192), 16, 0, 0); } while (0)
; #define PG8_LDA(dst, b, h) do { _Pragma("unroll") for (int m = 0; m < 4; ++m) _Pragma("unroll") for (int k = 0; k < 2; ++k) dst[m][k] = *(const PG8_LAS bf16x8*)(lds + PG8_SA(b, h) + aoff + m * 2048 + k * 1024); } while (0)
; #define PG8_MMA(ai, bj, At, Bt) do { __builtin_amdgcn_s_setprio(1); _Pragma("unroll") for (int m = 0; m < 4; ++m) _Pragma("unroll") for (int n = 0; n < 2; ++n) _Pragma("unroll") for (int k = 0; k < 2; ++k) \
;         acc[ai][bj][m][n] = __builtin_amdgcn_mfma_f32_16x16x32_bf16(Bt[n][k], At[m][k], acc[ai][bj][m][n], 0, 0, 0); __builtin_amdgcn_s_setprio(0); } while (0)
; #define PG8_WAIT_V(n) asm volatile("s_waitcnt vmcnt(" #n ")" ::: "memory")
; #define PG8_WAIT_L(n) asm volatile("s_waitcnt lgkmcnt(" #n ")" ::: "memory")
; #define PG8_BAR __builtin_amdgcn_s_barrier()
; #define PG8_SCHED __builtin_amdgcn_sched_barrier(0)
; template <class Epi, class Sched, bool ALIGN_EPI = false, bool SP2 = false>
; __device__ __forceinline__ void gemm_phase(PG8_LAS unsigned char* lds, const Gemm g, const Sched& S, const Epi& E) {
;     ...
;         for (int t = 0; t < nt; t += 2) {
;     ...
;             PG8_LDA(At, 1, 1); PG8_STAGE(PG8_SB(1, 0), b3, voffB); PG8_STAGE(PG8_SB(1, 1), b3 + hstep, voffB); PG8_STAGE(PG8_SA(1, 0), a3, voffA);
;             PG8_WAIT_V(8); PG8_WAIT_L(0); PG8_BAR; PG8_MMA(1, 0, At, B0); PG8_MMA(1, 1, At, B1); PG8_BAR; PG8_SCHED;
;     ...
;     if constexpr (!ALIGN_EPI) { if (wr == 0) PG8_BAR; }
	s_add_i32 s30, s52, s35
	v_lshl_add_u64 v[150:151], v[150:151], 0, s[74:75]
	s_mov_b32 m0, s30
	ds_read_b128 v[188:191], v145 offset:49152
	ds_read_b128 v[192:195], v145 offset:50176
	ds_read_b128 v[196:199], v145 offset:51200
	ds_read_b128 v[200:203], v145 offset:52224
	ds_read_b128 v[204:207], v145 offset:53248
	ds_read_b128 v[208:211], v145 offset:54272
	ds_read_b128 v[212:215], v145 offset:55296
	ds_read_b128 v[216:219], v145 offset:56320
	global_load_lds_dwordx4 v[150:151], off
	s_add_i32 m0, s30, 0x2000
	s_add_u32 s28, s28, 0x80080
	v_lshl_add_u64 v[150:151], v[220:221], 0, s[74:75]
	s_addc_u32 s29, s29, 0
	s_add_i32 s30, s53, s35
	global_load_lds_dwordx4 v[150:151], off
	v_lshl_add_u64 v[150:151], s[28:29], 0, v[152:153]
	s_mov_b32 m0, s30
	s_nop 0
	global_load_lds_dwordx4 v[150:151], off
	v_lshl_add_u64 v[150:151], s[28:29], 0, v[128:129]
	s_add_i32 m0, s30, 0x2000
	s_nop 0
	global_load_lds_dwordx4 v[150:151], off
	v_lshl_add_u64 v[150:151], v[222:223], 0, s[74:75]
	s_mov_b32 m0, s42
	s_nop 0
	global_load_lds_dwordx4 v[150:151], off
	v_lshl_add_u64 v[150:151], v[224:225], 0, s[74:75]
	s_mov_b32 m0, s43
	s_nop 0
	global_load_lds_dwordx4 v[150:151], off
	s_waitcnt vmcnt(8)
	s_waitcnt lgkmcnt(0)
	s_setprio 1
	s_barrier
	v_mfma_f32_16x16x32_bf16 v[60:63], v[138:141], v[188:191], v[60:63]
	v_mfma_f32_16x16x32_bf16 v[56:59], v[164:167], v[188:191], v[56:59]
	v_mfma_f32_16x16x32_bf16 v[44:47], v[138:141], v[196:199], v[44:47]
	v_mfma_f32_16x16x32_bf16 v[40:43], v[164:167], v[196:199], v[40:43]
	v_mfma_f32_16x16x32_bf16 v[28:31], v[138:141], v[204:207], v[28:31]
	v_mfma_f32_16x16x32_bf16 v[24:27], v[164:167], v[204:207], v[24:27]
	v_mfma_f32_16x16x32_bf16 v[12:15], v[138:141], v[212:215], v[12:15]
	v_mfma_f32_16x16x32_bf16 v[8:11], v[164:167], v[212:215], v[8:11]
	v_mfma_f32_16x16x32_bf16 v[60:63], v[146:149], v[192:195], v[60:63]
	v_mfma_f32_16x16x32_bf16 v[56:59], v[168:171], v[192:195], v[56:59]
	v_mfma_f32_16x16x32_bf16 v[44:47], v[146:149], v[200:203], v[44:47]
	v_mfma_f32_16x16x32_bf16 v[40:43], v[168:171], v[200:203], v[40:43]
	v_mfma_f32_16x16x32_bf16 v[28:31], v[146:149], v[208:211], v[28:31]
	v_mfma_f32_16x16x32_bf16 v[24:27], v[168:171], v[208:211], v[24:27]
	v_mfma_f32_16x16x32_bf16 v[12:15], v[146:149], v[216:219], v[12:15]
	v_mfma_f32_16x16x32_bf16 v[8:11], v[168:171], v[216:219], v[8:11]
	s_setprio 0
	s_setprio 1
	v_mfma_f32_16x16x32_bf16 v[52:55], v[172:175], v[188:191], v[52:55]
	v_mfma_f32_16x16x32_bf16 v[48:51], v[180:183], v[188:191], v[48:51]
	v_mfma_f32_16x16x32_bf16 v[36:39], v[172:175], v[196:199], v[36:39]
	v_mfma_f32_16x16x32_bf16 v[32:35], v[180:183], v[196:199], v[32:35]
	v_mfma_f32_16x16x32_bf16 v[20:23], v[172:175], v[204:207], v[20:23]
	v_mfma_f32_16x16x32_bf16 v[16:19], v[180:183], v[204:207], v[16:19]
	v_mfma_f32_16x16x32_bf16 v[4:7], v[172:175], v[212:215], v[4:7]
	v_mfma_f32_16x16x32_bf16 v[0:3], v[180:183], v[212:215], v[0:3]
	v_mfma_f32_16x16x32_bf16 v[52:55], v[176:179], v[192:195], v[52:55]
	v_mfma_f32_16x16x32_bf16 v[48:51], v[184:187], v[192:195], v[48:51]
	v_mfma_f32_16x16x32_bf16 v[36:39], v[176:179], v[200:203], v[36:39]
	v_mfma_f32_16x16x32_bf16 v[32:35], v[184:187], v[200:203], v[32:35]
	v_mfma_f32_16x16x32_bf16 v[20:23], v[176:179], v[208:211], v[20:23]
	v_mfma_f32_16x16x32_bf16 v[16:19], v[184:187], v[208:211], v[16:19]
	v_mfma_f32_16x16x32_bf16 v[4:7], v[176:179], v[216:219], v[4:7]
	v_mfma_f32_16x16x32_bf16 v[0:3], v[184:187], v[216:219], v[0:3]
	s_setprio 0
	s_barrier
	s_add_i32 s51, s51, 2
	s_add_u32 s26, s26, 0x100
	s_addc_u32 s27, s27, 0
	s_add_u32 s49, s49, 0x100
	s_addc_u32 s50, s50, 0
	s_cmp_gt_u32 s51, 29
	s_cbranch_scc0 .LBB0_1058
	s_and_b64 vcc, exec, s[16:17]
	s_cbranch_vccz .LBB0_1061
	s_barrier

; #define PG8_STAGE(bufoff, gbase, voff) do { _Pragma("unroll") for (int _i = 0; _i < 2; ++_i) \
;         __builtin_amdgcn_global_load_lds((const unsigned*)((const char*)(gbase) + (voff)[_i]), (PG8_LAS unsigned*)(lds + (bufoff) + ldsw + _i * 8192), 16, 0, 0); } while (0)
; #define PG8_WAIT_V(n) asm volatile("s_waitcnt vmcnt(" #n ")" ::: "memory")
; #define PG8_BAR __builtin_amdgcn_s_barrier()
; template <class Epi, class Sched, bool ALIGN_EPI = false, bool SP2 = false>
; __device__ __forceinline__ void gemm_phase(PG8_LAS unsigned char* lds, const Gemm g, const Sched& S, const Epi& E) {
;     ...
;     const int aoff = lds_byte(wr * 64 + fr, fq * 8), boff = lds_byte(wc * 32 + fr, fq * 8);
;     ...
;     f32x4 acc[2][2][4][2];
; #pragma unroll
;     for (int a = 0; a < 2; ++a)
; #pragma unroll
;         for (int b = 0; b < 2; ++b)
; #pragma unroll
;             for (int m = 0; m < 4; ++m)
; #pragma unroll
;                 for (int n = 0; n < 2; ++n) acc[a][b][m][n] = (f32x4){0.f, 0.f, 0.f, 0.f};
;     ...
;         PG8_WAIT_V(2); PG8_BAR;
;         PG8_STAGE(PG8_SB(1, 0), cB + kstep, voffB); PG8_STAGE(PG8_SA(1, 0), cA + kstep, voffA); PG8_STAGE(PG8_SB(1, 1), cB + hstep + kstep, voffB);
;         PG8_WAIT_V(6); PG8_BAR;
.LBB0_1159:
	v_lshl_add_u64 v[6:7], s[22:23], 0, v[152:153]
	v_mov_b32_e32 v33, v153
	v_lshl_add_u64 v[8:9], s[22:23], 0, v[32:33]
	v_mov_b32_e32 v41, v153
	s_and_b32 s34, s5, 3
	s_add_i32 m0, s35, 0x18000
	v_lshl_add_u64 v[6:7], v[6:7], 0, s[74:75]
	v_lshl_add_u64 v[10:11], s[2:3], 0, v[40:41]
	v_mov_b32_e32 v35, v153
	s_lshl_b32 s36, s4, 6
	s_lshl_b32 s4, s4, 13
	s_lshl_b32 s5, s34, 12
	s_waitcnt vmcnt(2)
	s_barrier
	global_load_lds_dwordx4 v[6:7], off
	v_lshl_add_u64 v[6:7], v[8:9], 0, s[74:75]
	s_add_i32 m0, s35, 0x1a000
	s_add_i32 s40, s35, 0x8000
	s_add_i32 s41, s35, 0xa000
	v_lshl_add_u64 v[12:13], s[2:3], 0, v[34:35]
	global_load_lds_dwordx4 v[6:7], off
	v_lshl_add_u64 v[6:7], v[10:11], 0, s[74:75]
	s_mov_b32 m0, s40
	s_add_u32 s0, s22, 0x200080
	global_load_lds_dwordx4 v[6:7], off
	v_lshl_add_u64 v[6:7], v[12:13], 0, s[74:75]
	s_mov_b32 m0, s41
	s_addc_u32 s1, s23, 0
	global_load_lds_dwordx4 v[6:7], off
	s_add_i32 m0, s35, 0x1c000
	v_lshl_add_u64 v[6:7], s[0:1], 0, v[152:153]
	global_load_lds_dwordx4 v[6:7], off
	v_lshl_add_u64 v[6:7], s[0:1], 0, v[32:33]
	s_add_i32 m0, s35, 0x1e000
	v_and_b32_e32 v144, 15, v234
	global_load_lds_dwordx4 v[6:7], off
	v_and_b32_e32 v6, 48, v234
	v_lshlrev_b32_e32 v7, 2, v234
	v_lshl_or_b32 v6, v144, 6, v6
	v_and_b32_e32 v7, 32, v7
	v_bitop3_b32 v8, v6, s4, v7 bitop3:0xde
	v_bitop3_b32 v50, v6, s5, v7 bitop3:0xde
	v_lshlrev_b32_e32 v6, 17, v4
	v_and_b32_e32 v6, 0xfffc0000, v6
	v_lshl_add_u32 v3, v3, 14, v6
	v_and_b32_e32 v4, 1, v4
	v_lshl_or_b32 v3, v4, 6, v3
	v_lshl_add_u32 v42, v5, 1, v3
	v_lshlrev_b32_e32 v3, 17, v0
	v_and_b32_e32 v3, 0xfffc0000, v3
	v_lshl_add_u32 v1, v1, 14, v3
	v_and_b32_e32 v0, 1, v0
	v_lshl_or_b32 v0, v0, 6, v1
	s_waitcnt vmcnt(6)
	v_lshl_add_u32 v44, v2, 1, v0
	v_mov_b32_e32 v2, v153
	v_mov_b32_e32 v3, v153
	v_readlane_b32 s0, v253, 27
	v_mov_b32_e32 v0, v153
	v_mov_b32_e32 v1, v153
	v_add_u32_e32 v51, 0, v8
	v_mov_b64_e32 v[6:7], v[2:3]
	v_mov_b64_e32 v[18:19], v[2:3]
	v_mov_b64_e32 v[22:23], v[2:3]
	v_mov_b64_e32 v[38:39], v[2:3]
	v_mov_b64_e32 v[54:55], v[2:3]
	v_mov_b64_e32 v[66:67], v[2:3]
	v_mov_b64_e32 v[70:71], v[2:3]
	v_mov_b64_e32 v[10:11], v[2:3]
	v_mov_b64_e32 v[14:15], v[2:3]
	v_mov_b64_e32 v[26:27], v[2:3]
	v_mov_b64_e32 v[30:31], v[2:3]
	v_mov_b64_e32 v[58:59], v[2:3]
	v_mov_b64_e32 v[62:63], v[2:3]
	v_mov_b64_e32 v[74:75], v[2:3]
	v_mov_b64_e32 v[78:79], v[2:3]
	v_mov_b64_e32 v[82:83], v[2:3]
	v_mov_b64_e32 v[86:87], v[2:3]
	v_mov_b64_e32 v[98:99], v[2:3]
	v_mov_b64_e32 v[102:103], v[2:3]
	v_mov_b64_e32 v[114:115], v[2:3]
	v_mov_b64_e32 v[118:119], v[2:3]
	v_mov_b64_e32 v[130:131], v[2:3]
	v_mov_b64_e32 v[134:135], v[2:3]
	v_mov_b64_e32 v[90:91], v[2:3]
	v_mov_b64_e32 v[94:95], v[2:3]
	v_mov_b64_e32 v[106:107], v[2:3]
	v_mov_b64_e32 v[110:111], v[2:3]
	v_mov_b64_e32 v[122:123], v[2:3]
	v_mov_b64_e32 v[126:127], v[2:3]
	v_mov_b64_e32 v[138:139], v[2:3]
	v_mov_b64_e32 v[142:143], v[2:3]
	s_mov_b32 s6, s0
	v_readlane_b32 s0, v253, 39
	v_mov_b32_e32 v43, v153
	v_mov_b32_e32 v45, v153
	s_mov_b32 s43, 0
	v_mov_b64_e32 v[4:5], v[0:1]
	v_mov_b64_e32 v[16:17], v[0:1]
	v_mov_b64_e32 v[20:21], v[0:1]
	v_mov_b64_e32 v[36:37], v[0:1]
	v_mov_b64_e32 v[52:53], v[0:1]
	v_mov_b64_e32 v[64:65], v[0:1]
	v_mov_b64_e32 v[68:69], v[0:1]
	v_mov_b64_e32 v[8:9], v[0:1]
	v_mov_b64_e32 v[12:13], v[0:1]
	v_mov_b64_e32 v[24:25], v[0:1]
	v_mov_b64_e32 v[28:29], v[0:1]
	v_mov_b64_e32 v[56:57], v[0:1]
	v_mov_b64_e32 v[60:61], v[0:1]
	v_mov_b64_e32 v[72:73], v[0:1]
	v_mov_b64_e32 v[76:77], v[0:1]
	v_mov_b64_e32 v[80:81], v[0:1]
	v_mov_b64_e32 v[84:85], v[0:1]
	v_mov_b64_e32 v[96:97], v[0:1]
	v_mov_b64_e32 v[100:101], v[0:1]
	v_mov_b64_e32 v[112:113], v[0:1]
	v_mov_b64_e32 v[116:117], v[0:1]
	v_mov_b64_e32 v[128:129], v[0:1]
	v_mov_b64_e32 v[132:133], v[0:1]
	v_mov_b64_e32 v[88:89], v[0:1]
	v_mov_b64_e32 v[92:93], v[0:1]
	v_mov_b64_e32 v[104:105], v[0:1]
	v_mov_b64_e32 v[108:109], v[0:1]
	v_mov_b64_e32 v[120:121], v[0:1]
	v_mov_b64_e32 v[124:125], v[0:1]
	v_mov_b64_e32 v[136:137], v[0:1]
	v_mov_b64_e32 v[140:141], v[0:1]
	s_mov_b32 s42, s0
	s_barrier
	v_readlane_b32 s1, v253, 40
	s_branch .LBB0_1162
	s_nop 0
	s_nop 0
	s_nop 0
	s_nop 0

; #define PG8_STAGE(bufoff, gbase, voff) do { _Pragma("unroll") for (int _i = 0; _i < 2; ++_i) \
;         __builtin_amdgcn_global_load_lds((const unsigned*)((const char*)(gbase) + (voff)[_i]), (PG8_LAS unsigned*)(lds + (bufoff) + ldsw + _i * 8192), 16, 0, 0); } while (0)
; #define PG8_LDA(dst, b, h) do { _Pragma("unroll") for (int m = 0; m < 4; ++m) _Pragma("unroll") for (int k = 0; k < 2; ++k) dst[m][k] = *(const PG8_LAS bf16x8*)(lds + PG8_SA(b, h) + aoff + m * 2048 + k * 1024); } while (0)
; #define PG8_LDB(dst, b, h) do { _Pragma("unroll") for (int n = 0; n < 2; ++n) _Pragma("unroll") for (int k = 0; k < 2; ++k) dst[n][k] = *(const PG8_LAS bf16x8*)(lds + PG8_SB(b, h) + boff + n * 2048 + k * 1024); } while (0)
; #define PG8_MMA(ai, bj, At, Bt) do { __builtin_amdgcn_s_setprio(1); _Pragma("unroll") for (int m = 0; m < 4; ++m) _Pragma("unroll") for (int n = 0; n < 2; ++n) _Pragma("unroll") for (int k = 0; k < 2; ++k) \
;         acc[ai][bj][m][n] = __builtin_amdgcn_mfma_f32_16x16x32_bf16(Bt[n][k], At[m][k], acc[ai][bj][m][n], 0, 0, 0); __builtin_amdgcn_s_setprio(0); } while (0)
; #define PG8_WAIT_V(n) asm volatile("s_waitcnt vmcnt(" #n ")" ::: "memory")
; #define PG8_BAR __builtin_amdgcn_s_barrier()
; template <class Epi, class Sched, bool ALIGN_EPI = false, bool SP2 = false>
; __device__ __forceinline__ void gemm_phase(PG8_LAS unsigned char* lds, const Gemm g, const Sched& S, const Epi& E) {
;     ...
;         for (int t = 0; t < nt; t += 2) {
;             const bool last = (t == nt - 2);
;             const char* a1 = cA + (size_t)(t + 1) * kstep;
;             const char* a2 = last ? nA : cA + (size_t)(t + 2) * kstep; const char* b2 = last ? nB : cB + (size_t)(t + 2) * kstep;
;             const char* a3 = a2 + kstep; const char* b3 = b2 + kstep;
;             if (last && has_next) S.a_ready(nxt);
;             if constexpr (SP2) {
;             PG8_LDB(B0, 0, 0); PG8_LDB(B1, 0, 1); PG8_SCHED; PG8_LDA(At, 0, 0); PG8_STAGE(PG8_SA(1, 1), a1 + hstep, voffA);
;             PG8_WAIT_V(8); PG8_WAIT_L(0); PG8_BAR; PG8_MMA(0, 0, At, B0); PG8_MMA(0, 1, At, B1); PG8_BAR; PG8_SCHED;
;             PG8_LDA(At, 0, 1); PG8_STAGE(PG8_SB(0, 0), b2, voffB); PG8_STAGE(PG8_SB(0, 1), b2 + hstep, voffB); PG8_STAGE(PG8_SA(0, 0), a2, voffA);
;             PG8_WAIT_V(8); PG8_WAIT_L(0); PG8_BAR; PG8_MMA(1, 0, At, B0); PG8_MMA(1, 1, At, B1); PG8_BAR; PG8_SCHED;
.LBB0_1169:
	s_add_u32 s24, s2, s22
	s_addc_u32 s25, s3, s23
	s_add_u32 s24, s24, 0x100
	s_addc_u32 s25, s25, 0
	s_add_u32 s50, s45, s22
	s_addc_u32 s51, s46, s23
	s_add_i32 s52, 0, 0x10000
	s_cmpk_eq_i32 s22, 0x3f00
	s_cselect_b32 s27, s17, s25
	s_cselect_b32 s26, s47, s24
	v_add_u32_e32 v145, s52, v50
	s_cselect_b32 s25, s15, s51
	s_cselect_b32 s24, s48, s50
	s_add_i32 s53, 0, 0x14000
	ds_read_b128 v[146:149], v145
	ds_read_b128 v[164:167], v145 offset:1024
	ds_read_b128 v[168:171], v145 offset:2048
	ds_read_b128 v[172:175], v145 offset:3072
	v_add_u32_e32 v145, s53, v50
	ds_read_b128 v[176:179], v145
	ds_read_b128 v[180:183], v145 offset:1024
	ds_read_b128 v[184:187], v145 offset:2048
	ds_read_b128 v[188:191], v145 offset:3072
	v_lshl_add_u64 v[150:151], v[46:47], 0, s[22:23]
	s_add_i32 m0, s35, 0xc000
	ds_read_b128 v[192:195], v51
	ds_read_b128 v[196:199], v51 offset:1024
	ds_read_b128 v[200:203], v51 offset:2048
	ds_read_b128 v[204:207], v51 offset:3072
	ds_read_b128 v[208:211], v51 offset:4096
	ds_read_b128 v[212:215], v51 offset:5120
	ds_read_b128 v[216:219], v51 offset:6144
	ds_read_b128 v[220:223], v51 offset:7168
	global_load_lds_dwordx4 v[150:151], off
	v_lshl_add_u64 v[150:151], v[48:49], 0, s[22:23]
	s_add_i32 m0, s35, 0xe000
	s_nop 0
	global_load_lds_dwordx4 v[150:151], off
	s_waitcnt vmcnt(8)
	s_waitcnt lgkmcnt(0)
	s_setprio 1
	s_barrier
	v_mfma_f32_16x16x32_bf16 v[140:143], v[146:149], v[192:195], v[140:143]
	v_mfma_f32_16x16x32_bf16 v[136:139], v[168:171], v[192:195], v[136:139]
	v_mfma_f32_16x16x32_bf16 v[124:127], v[146:149], v[200:203], v[124:127]
	v_mfma_f32_16x16x32_bf16 v[120:123], v[168:171], v[200:203], v[120:123]
	v_mfma_f32_16x16x32_bf16 v[108:111], v[146:149], v[208:211], v[108:111]
	v_mfma_f32_16x16x32_bf16 v[104:107], v[168:171], v[208:211], v[104:107]
	v_mfma_f32_16x16x32_bf16 v[92:95], v[146:149], v[216:219], v[92:95]
	v_mfma_f32_16x16x32_bf16 v[88:91], v[168:171], v[216:219], v[88:91]
	v_mfma_f32_16x16x32_bf16 v[140:143], v[164:167], v[196:199], v[140:143]
	v_mfma_f32_16x16x32_bf16 v[136:139], v[172:175], v[196:199], v[136:139]
	v_mfma_f32_16x16x32_bf16 v[124:127], v[164:167], v[204:207], v[124:127]
	v_mfma_f32_16x16x32_bf16 v[120:123], v[172:175], v[204:207], v[120:123]
	v_mfma_f32_16x16x32_bf16 v[108:111], v[164:167], v[212:215], v[108:111]
	v_mfma_f32_16x16x32_bf16 v[104:107], v[172:175], v[212:215], v[104:107]
	v_mfma_f32_16x16x32_bf16 v[92:95], v[164:167], v[220:223], v[92:95]
	v_mfma_f32_16x16x32_bf16 v[88:91], v[172:175], v[220:223], v[88:91]
	s_setprio 0
	s_setprio 1
	v_mfma_f32_16x16x32_bf16 v[132:135], v[176:179], v[192:195], v[132:135]
	v_mfma_f32_16x16x32_bf16 v[128:131], v[184:187], v[192:195], v[128:131]
	v_mfma_f32_16x16x32_bf16 v[116:119], v[176:179], v[200:203], v[116:119]
	v_mfma_f32_16x16x32_bf16 v[112:115], v[184:187], v[200:203], v[112:115]
	v_mfma_f32_16x16x32_bf16 v[100:103], v[176:179], v[208:211], v[100:103]
	v_mfma_f32_16x16x32_bf16 v[96:99], v[184:187], v[208:211], v[96:99]
	v_mfma_f32_16x16x32_bf16 v[84:87], v[176:179], v[216:219], v[84:87]
	v_mfma_f32_16x16x32_bf16 v[80:83], v[184:187], v[216:219], v[80:83]
	v_mfma_f32_16x16x32_bf16 v[132:135], v[180:183], v[196:199], v[132:135]
	v_mfma_f32_16x16x32_bf16 v[128:131], v[188:191], v[196:199], v[128:131]
	v_mfma_f32_16x16x32_bf16 v[116:119], v[180:183], v[204:207], v[116:119]
	v_mfma_f32_16x16x32_bf16 v[112:115], v[188:191], v[204:207], v[112:115]
	v_mfma_f32_16x16x32_bf16 v[100:103], v[180:183], v[212:215], v[100:103]
	v_mfma_f32_16x16x32_bf16 v[96:99], v[188:191], v[212:215], v[96:99]
	v_mfma_f32_16x16x32_bf16 v[84:87], v[180:183], v[220:223], v[84:87]
	v_mfma_f32_16x16x32_bf16 v[80:83], v[188:191], v[220:223], v[80:83]
	s_setprio 0
	s_barrier
	s_add_i32 s50, s52, s33
	v_lshl_add_u64 v[150:151], s[24:25], 0, v[152:153]
	s_mov_b32 m0, s50
	ds_read_b128 v[192:195], v51 offset:16384
	ds_read_b128 v[196:199], v51 offset:17408
	ds_read_b128 v[200:203], v51 offset:18432
	ds_read_b128 v[204:207], v51 offset:19456
	ds_read_b128 v[208:211], v51 offset:20480
	ds_read_b128 v[212:215], v51 offset:21504
	ds_read_b128 v[216:219], v51 offset:22528
	ds_read_b128 v[220:223], v51 offset:23552
	global_load_lds_dwordx4 v[150:151], off
	s_add_i32 m0, s50, 0x2000
	s_add_u32 s50, s24, 0x200000
	v_lshl_add_u64 v[224:225], s[24:25], 0, v[32:33]
	s_addc_u32 s51, s25, 0
	s_add_i32 s52, s53, s33
	global_load_lds_dwordx4 v[224:225], off
	v_lshl_add_u64 v[226:227], s[50:51], 0, v[152:153]
	s_mov_b32 m0, s52
	v_lshl_add_u64 v[228:229], s[26:27], 0, v[34:35]
	global_load_lds_dwordx4 v[226:227], off
	v_lshl_add_u64 v[226:227], s[50:51], 0, v[32:33]
	s_add_i32 m0, s52, 0x2000
	s_nop 0
	global_load_lds_dwordx4 v[226:227], off
	v_lshl_add_u64 v[226:227], s[26:27], 0, v[40:41]
	s_mov_b32 m0, s35
	s_nop 0
	global_load_lds_dwordx4 v[226:227], off
	s_mov_b32 m0, s37
	s_nop 0
	global_load_lds_dwordx4 v[228:229], off
	s_waitcnt vmcnt(8)
	s_waitcnt lgkmcnt(0)
	s_setprio 1
	s_barrier
; #define PG8_STAGE(bufoff, gbase, voff) do { _Pragma("unroll") for (int _i = 0; _i < 2; ++_i) \
;         __builtin_amdgcn_global_load_lds((const unsigned*)((const char*)(gbase) + (voff)[_i]), (PG8_LAS unsigned*)(lds + (bufoff) + ldsw + _i * 8192), 16, 0, 0); } while (0)
; #define PG8_LDA(dst, b, h) do { _Pragma("unroll") for (int m = 0; m < 4; ++m) _Pragma("unroll") for (int k = 0; k < 2; ++k) dst[m][k] = *(const PG8_LAS bf16x8*)(lds + PG8_SA(b, h) + aoff + m * 2048 + k * 1024); } while (0)
; #define PG8_LDB(dst, b, h) do { _Pragma("unroll") for (int n = 0; n < 2; ++n) _Pragma("unroll") for (int k = 0; k < 2; ++k) dst[n][k] = *(const PG8_LAS bf16x8*)(lds + PG8_SB(b, h) + boff + n * 2048 + k * 1024); } while (0)
; #define PG8_MMA(ai, bj, At, Bt) do { __builtin_amdgcn_s_setprio(1); _Pragma("unroll") for (int m = 0; m < 4; ++m) _Pragma("unroll") for (int n = 0; n < 2; ++n) _Pragma("unroll") for (int k = 0; k < 2; ++k) \
;         acc[ai][bj][m][n] = __builtin_amdgcn_mfma_f32_16x16x32_bf16(Bt[n][k], At[m][k], acc[ai][bj][m][n], 0, 0, 0); __builtin_amdgcn_s_setprio(0); } while (0)
; #define PG8_WAIT_V(n) asm volatile("s_waitcnt vmcnt(" #n ")" ::: "memory")
; #define PG8_WAIT_L(n) asm volatile("s_waitcnt lgkmcnt(" #n ")" ::: "memory")
; #define PG8_BAR __builtin_amdgcn_s_barrier()
; #define PG8_SCHED __builtin_amdgcn_sched_barrier(0)
; template <class Epi, class Sched, bool ALIGN_EPI = false, bool SP2 = false>
; __device__ __forceinline__ void gemm_phase(PG8_LAS unsigned char* lds, const Gemm g, const Sched& S, const Epi& E) {
;     ...
;             PG8_WAIT_V(8); PG8_WAIT_L(0); PG8_BAR; PG8_MMA(1, 0, At, B0); PG8_MMA(1, 1, At, B1); PG8_BAR; PG8_SCHED;
;             PG8_LDB(B0, 1, 0); PG8_LDB(B1, 1, 1); PG8_SCHED; PG8_LDA(At, 1, 0); PG8_STAGE(PG8_SA(0, 1), a2 + hstep, voffA);
;             PG8_WAIT_V(8); PG8_WAIT_L(0); PG8_BAR; PG8_MMA(0, 0, At, B0); PG8_MMA(0, 1, At, B1); PG8_BAR; PG8_SCHED;
	v_mfma_f32_16x16x32_bf16 v[76:79], v[146:149], v[192:195], v[76:79]
	v_mfma_f32_16x16x32_bf16 v[72:75], v[168:171], v[192:195], v[72:75]
	v_mfma_f32_16x16x32_bf16 v[60:63], v[146:149], v[200:203], v[60:63]
	v_mfma_f32_16x16x32_bf16 v[56:59], v[168:171], v[200:203], v[56:59]
	v_mfma_f32_16x16x32_bf16 v[28:31], v[146:149], v[208:211], v[28:31]
	v_mfma_f32_16x16x32_bf16 v[24:27], v[168:171], v[208:211], v[24:27]
	v_mfma_f32_16x16x32_bf16 v[12:15], v[146:149], v[216:219], v[12:15]
	v_mfma_f32_16x16x32_bf16 v[8:11], v[168:171], v[216:219], v[8:11]
	v_mfma_f32_16x16x32_bf16 v[76:79], v[164:167], v[196:199], v[76:79]
	v_mfma_f32_16x16x32_bf16 v[72:75], v[172:175], v[196:199], v[72:75]
	v_mfma_f32_16x16x32_bf16 v[60:63], v[164:167], v[204:207], v[60:63]
	v_mfma_f32_16x16x32_bf16 v[56:59], v[172:175], v[204:207], v[56:59]
	v_mfma_f32_16x16x32_bf16 v[28:31], v[164:167], v[212:215], v[28:31]
	v_mfma_f32_16x16x32_bf16 v[24:27], v[172:175], v[212:215], v[24:27]
	v_mfma_f32_16x16x32_bf16 v[12:15], v[164:167], v[220:223], v[12:15]
	v_mfma_f32_16x16x32_bf16 v[8:11], v[172:175], v[220:223], v[8:11]
	s_setprio 0
	s_setprio 1
	v_mfma_f32_16x16x32_bf16 v[68:71], v[176:179], v[192:195], v[68:71]
	v_mfma_f32_16x16x32_bf16 v[64:67], v[184:187], v[192:195], v[64:67]
	v_mfma_f32_16x16x32_bf16 v[52:55], v[176:179], v[200:203], v[52:55]
	v_mfma_f32_16x16x32_bf16 v[36:39], v[184:187], v[200:203], v[36:39]
	v_mfma_f32_16x16x32_bf16 v[20:23], v[176:179], v[208:211], v[20:23]
	v_mfma_f32_16x16x32_bf16 v[16:19], v[184:187], v[208:211], v[16:19]
	v_mfma_f32_16x16x32_bf16 v[4:7], v[176:179], v[216:219], v[4:7]
	v_mfma_f32_16x16x32_bf16 v[0:3], v[184:187], v[216:219], v[0:3]
	v_mfma_f32_16x16x32_bf16 v[68:71], v[180:183], v[196:199], v[68:71]
	v_mfma_f32_16x16x32_bf16 v[64:67], v[188:191], v[196:199], v[64:67]
	v_mfma_f32_16x16x32_bf16 v[52:55], v[180:183], v[204:207], v[52:55]
	v_mfma_f32_16x16x32_bf16 v[36:39], v[188:191], v[204:207], v[36:39]
	v_mfma_f32_16x16x32_bf16 v[20:23], v[180:183], v[212:215], v[20:23]
	v_mfma_f32_16x16x32_bf16 v[16:19], v[188:191], v[212:215], v[16:19]
	v_mfma_f32_16x16x32_bf16 v[4:7], v[180:183], v[220:223], v[4:7]
	v_mfma_f32_16x16x32_bf16 v[0:3], v[188:191], v[220:223], v[0:3]
	s_setprio 0
	s_barrier
	s_add_i32 s50, 0, 0x18000
	v_add_u32_e32 v145, s50, v50
	s_add_i32 s51, 0, 0x1c000
	ds_read_b128 v[146:149], v145
	ds_read_b128 v[164:167], v145 offset:1024
	ds_read_b128 v[168:171], v145 offset:2048
	ds_read_b128 v[172:175], v145 offset:3072
	v_add_u32_e32 v145, s51, v50
	ds_read_b128 v[176:179], v145
	ds_read_b128 v[180:183], v145 offset:1024
	ds_read_b128 v[184:187], v145 offset:2048
	ds_read_b128 v[188:191], v145 offset:3072
	s_add_u32 s26, s26, 0x200000
	s_addc_u32 s27, s27, 0
	s_mov_b32 m0, s38
	v_lshl_add_u64 v[230:231], s[26:27], 0, v[40:41]
	ds_read_b128 v[192:195], v51 offset:32768
	ds_read_b128 v[196:199], v51 offset:33792
	ds_read_b128 v[200:203], v51 offset:34816
	ds_read_b128 v[204:207], v51 offset:35840
	ds_read_b128 v[208:211], v51 offset:36864
	ds_read_b128 v[212:215], v51 offset:37888
	ds_read_b128 v[216:219], v51 offset:38912
	ds_read_b128 v[220:223], v51 offset:39936
	global_load_lds_dwordx4 v[230:231], off
	v_lshl_add_u64 v[230:231], s[26:27], 0, v[34:35]
	s_mov_b32 m0, s39
	s_nop 0
	global_load_lds_dwordx4 v[230:231], off
	s_waitcnt vmcnt(8)
	s_waitcnt lgkmcnt(0)
	s_setprio 1
	s_barrier
	v_mfma_f32_16x16x32_bf16 v[140:143], v[146:149], v[192:195], v[140:143]
	v_mfma_f32_16x16x32_bf16 v[136:139], v[168:171], v[192:195], v[136:139]
	v_mfma_f32_16x16x32_bf16 v[124:127], v[146:149], v[200:203], v[124:127]
	v_mfma_f32_16x16x32_bf16 v[120:123], v[168:171], v[200:203], v[120:123]
	v_mfma_f32_16x16x32_bf16 v[108:111], v[146:149], v[208:211], v[108:111]
	v_mfma_f32_16x16x32_bf16 v[104:107], v[168:171], v[208:211], v[104:107]
	v_mfma_f32_16x16x32_bf16 v[92:95], v[146:149], v[216:219], v[92:95]
	v_mfma_f32_16x16x32_bf16 v[88:91], v[168:171], v[216:219], v[88:91]
	v_mfma_f32_16x16x32_bf16 v[140:143], v[164:167], v[196:199], v[140:143]
	v_mfma_f32_16x16x32_bf16 v[136:139], v[172:175], v[196:199], v[136:139]
	v_mfma_f32_16x16x32_bf16 v[124:127], v[164:167], v[204:207], v[124:127]
	v_mfma_f32_16x16x32_bf16 v[120:123], v[172:175], v[204:207], v[120:123]
	v_mfma_f32_16x16x32_bf16 v[108:111], v[164:167], v[212:215], v[108:111]
	v_mfma_f32_16x16x32_bf16 v[104:107], v[172:175], v[212:215], v[104:107]
	v_mfma_f32_16x16x32_bf16 v[92:95], v[164:167], v[220:223], v[92:95]
	v_mfma_f32_16x16x32_bf16 v[88:91], v[172:175], v[220:223], v[88:91]
	s_setprio 0
	s_setprio 1
	v_mfma_f32_16x16x32_bf16 v[132:135], v[176:179], v[192:195], v[132:135]
	v_mfma_f32_16x16x32_bf16 v[128:131], v[184:187], v[192:195], v[128:131]
	v_mfma_f32_16x16x32_bf16 v[116:119], v[176:179], v[200:203], v[116:119]
	v_mfma_f32_16x16x32_bf16 v[112:115], v[184:187], v[200:203], v[112:115]
	v_mfma_f32_16x16x32_bf16 v[100:103], v[176:179], v[208:211], v[100:103]
	v_mfma_f32_16x16x32_bf16 v[96:99], v[184:187], v[208:211], v[96:99]
	v_mfma_f32_16x16x32_bf16 v[84:87], v[176:179], v[216:219], v[84:87]
	v_mfma_f32_16x16x32_bf16 v[80:83], v[184:187], v[216:219], v[80:83]
	v_mfma_f32_16x16x32_bf16 v[132:135], v[180:183], v[196:199], v[132:135]
	v_mfma_f32_16x16x32_bf16 v[128:131], v[188:191], v[196:199], v[128:131]
	v_mfma_f32_16x16x32_bf16 v[116:119], v[180:183], v[204:207], v[116:119]
	v_mfma_f32_16x16x32_bf16 v[112:115], v[188:191], v[204:207], v[112:115]
	v_mfma_f32_16x16x32_bf16 v[100:103], v[180:183], v[212:215], v[100:103]
	v_mfma_f32_16x16x32_bf16 v[96:99], v[188:191], v[212:215], v[96:99]
	v_mfma_f32_16x16x32_bf16 v[84:87], v[180:183], v[220:223], v[84:87]
	v_mfma_f32_16x16x32_bf16 v[80:83], v[188:191], v[220:223], v[80:83]
	s_setprio 0
	s_barrier
; #define PG8_STAGE(bufoff, gbase, voff) do { _Pragma("unroll") for (int _i = 0; _i < 2; ++_i) \
;         __builtin_amdgcn_global_load_lds((const unsigned*)((const char*)(gbase) + (voff)[_i]), (PG8_LAS unsigned*)(lds + (bufoff) + ldsw + _i * 8192), 16, 0, 0); } while (0)
; #define PG8_LDA(dst, b, h) do { _Pragma("unroll") for (int m = 0; m < 4; ++m) _Pragma("unroll") for (int k = 0; k < 2; ++k) dst[m][k] = *(const PG8_LAS bf16x8*)(lds + PG8_SA(b, h) + aoff + m * 2048 + k * 1024); } while (0)
; #define PG8_MMA(ai, bj, At, Bt) do { __builtin_amdgcn_s_setprio(1); _Pragma("unroll") for (int m = 0; m < 4; ++m) _Pragma("unroll") for (int n = 0; n < 2; ++n) _Pragma("unroll") for (int k = 0; k < 2; ++k) \
;         acc[ai][bj][m][n] = __builtin_amdgcn_mfma_f32_16x16x32_bf16(Bt[n][k], At[m][k], acc[ai][bj][m][n], 0, 0, 0); __builtin_amdgcn_s_setprio(0); } while (0)
; #define PG8_WAIT_V(n) asm volatile("s_waitcnt vmcnt(" #n ")" ::: "memory")
; #define PG8_WAIT_L(n) asm volatile("s_waitcnt lgkmcnt(" #n ")" ::: "memory")
; #define PG8_BAR __builtin_amdgcn_s_barrier()
; #define PG8_SCHED __builtin_amdgcn_sched_barrier(0)
; template <class Epi, class Sched, bool ALIGN_EPI = false, bool SP2 = false>
; __device__ __forceinline__ void gemm_phase(PG8_LAS unsigned char* lds, const Gemm g, const Sched& S, const Epi& E) {
;     ...
;             PG8_LDA(At, 1, 1); PG8_STAGE(PG8_SB(1, 0), b3, voffB); PG8_STAGE(PG8_SB(1, 1), b3 + hstep, voffB); PG8_STAGE(PG8_SA(1, 0), a3, voffA);
;             PG8_WAIT_V(8); PG8_WAIT_L(0); PG8_BAR; PG8_MMA(1, 0, At, B0); PG8_MMA(1, 1, At, B1); PG8_BAR; PG8_SCHED;
;     ...
; #pragma unroll
;         for (int a = 0; a < 2; ++a)
; #pragma unroll
;             for (int b = 0; b < 2; ++b)
; #pragma unroll
;                 for (int m = 0; m < 4; ++m)
; #pragma unroll
;                     for (int n = 0; n < 2; ++n) acc[a][b][m][n] = (f32x4){0.f, 0.f, 0.f, 0.f};
;         cur = nxt; cA = nA; cB = nB; ++ui;
	s_add_i32 s26, s50, s33
	v_lshl_add_u64 v[150:151], v[150:151], 0, s[74:75]
	s_mov_b32 m0, s26
	ds_read_b128 v[192:195], v51 offset:49152
	ds_read_b128 v[196:199], v51 offset:50176
	ds_read_b128 v[200:203], v51 offset:51200
	ds_read_b128 v[204:207], v51 offset:52224
	ds_read_b128 v[208:211], v51 offset:53248
	ds_read_b128 v[212:215], v51 offset:54272
	ds_read_b128 v[216:219], v51 offset:55296
	ds_read_b128 v[220:223], v51 offset:56320
	global_load_lds_dwordx4 v[150:151], off
	s_add_i32 m0, s26, 0x2000
	s_add_u32 s24, s24, 0x200080
	v_lshl_add_u64 v[150:151], v[224:225], 0, s[74:75]
	s_addc_u32 s25, s25, 0
	s_add_i32 s26, s51, s33
	global_load_lds_dwordx4 v[150:151], off
	v_lshl_add_u64 v[150:151], s[24:25], 0, v[152:153]
	s_mov_b32 m0, s26
	s_nop 0
	global_load_lds_dwordx4 v[150:151], off
	v_lshl_add_u64 v[150:151], s[24:25], 0, v[32:33]
	s_add_i32 m0, s26, 0x2000
	s_nop 0
	global_load_lds_dwordx4 v[150:151], off
	v_lshl_add_u64 v[150:151], v[226:227], 0, s[74:75]
	s_mov_b32 m0, s40
	s_nop 0
	global_load_lds_dwordx4 v[150:151], off
	v_lshl_add_u64 v[150:151], v[228:229], 0, s[74:75]
	s_mov_b32 m0, s41
	s_nop 0
	global_load_lds_dwordx4 v[150:151], off
	s_waitcnt vmcnt(8)
	s_waitcnt lgkmcnt(0)
	s_setprio 1
	s_barrier
	v_mfma_f32_16x16x32_bf16 v[76:79], v[146:149], v[192:195], v[76:79]
	v_mfma_f32_16x16x32_bf16 v[72:75], v[168:171], v[192:195], v[72:75]
	v_mfma_f32_16x16x32_bf16 v[60:63], v[146:149], v[200:203], v[60:63]
	v_mfma_f32_16x16x32_bf16 v[56:59], v[168:171], v[200:203], v[56:59]
	v_mfma_f32_16x16x32_bf16 v[28:31], v[146:149], v[208:211], v[28:31]
	v_mfma_f32_16x16x32_bf16 v[24:27], v[168:171], v[208:211], v[24:27]
	v_mfma_f32_16x16x32_bf16 v[12:15], v[146:149], v[216:219], v[12:15]
	v_mfma_f32_16x16x32_bf16 v[8:11], v[168:171], v[216:219], v[8:11]
	v_mfma_f32_16x16x32_bf16 v[76:79], v[164:167], v[196:199], v[76:79]
	v_mfma_f32_16x16x32_bf16 v[72:75], v[172:175], v[196:199], v[72:75]
	v_mfma_f32_16x16x32_bf16 v[60:63], v[164:167], v[204:207], v[60:63]
	v_mfma_f32_16x16x32_bf16 v[56:59], v[172:175], v[204:207], v[56:59]
	v_mfma_f32_16x16x32_bf16 v[28:31], v[164:167], v[212:215], v[28:31]
	v_mfma_f32_16x16x32_bf16 v[24:27], v[172:175], v[212:215], v[24:27]
	v_mfma_f32_16x16x32_bf16 v[12:15], v[164:167], v[220:223], v[12:15]
	v_mfma_f32_16x16x32_bf16 v[8:11], v[172:175], v[220:223], v[8:11]
	s_setprio 0
	s_setprio 1
	v_mfma_f32_16x16x32_bf16 v[68:71], v[176:179], v[192:195], v[68:71]
	v_mfma_f32_16x16x32_bf16 v[64:67], v[184:187], v[192:195], v[64:67]
	v_mfma_f32_16x16x32_bf16 v[52:55], v[176:179], v[200:203], v[52:55]
	v_mfma_f32_16x16x32_bf16 v[36:39], v[184:187], v[200:203], v[36:39]
	v_mfma_f32_16x16x32_bf16 v[20:23], v[176:179], v[208:211], v[20:23]
	v_mfma_f32_16x16x32_bf16 v[16:19], v[184:187], v[208:211], v[16:19]
	v_mfma_f32_16x16x32_bf16 v[4:7], v[176:179], v[216:219], v[4:7]
	v_mfma_f32_16x16x32_bf16 v[0:3], v[184:187], v[216:219], v[0:3]
	v_mfma_f32_16x16x32_bf16 v[68:71], v[180:183], v[196:199], v[68:71]
	v_mfma_f32_16x16x32_bf16 v[64:67], v[188:191], v[196:199], v[64:67]
	v_mfma_f32_16x16x32_bf16 v[52:55], v[180:183], v[204:207], v[52:55]
	v_mfma_f32_16x16x32_bf16 v[36:39], v[188:191], v[204:207], v[36:39]
	v_mfma_f32_16x16x32_bf16 v[20:23], v[180:183], v[212:215], v[20:23]
	v_mfma_f32_16x16x32_bf16 v[16:19], v[188:191], v[212:215], v[16:19]
	v_mfma_f32_16x16x32_bf16 v[4:7], v[180:183], v[220:223], v[4:7]
	v_mfma_f32_16x16x32_bf16 v[0:3], v[188:191], v[220:223], v[0:3]
	s_setprio 0
	s_barrier
	s_add_i32 s49, s49, 2
	s_add_u32 s22, s22, 0x100
	s_addc_u32 s23, s23, 0
	s_cmpk_gt_u32 s49, 0x7d
	s_cbranch_scc0 .LBB0_1169
	s_add_u32 s22, s45, 0xffffff00
	s_addc_u32 s23, s46, -1
	s_andn2_b64 vcc, exec, s[4:5]
	s_cbranch_vccnz .LBB0_1160
	v_mov_b32_e32 v0, 0
	s_mov_b32 s6, s14
	s_mov_b32 s42, s16
	s_mov_b64 s[2:3], s[20:21]
	s_mov_b32 s43, s44
	v_mov_b32_e32 v1, v0
	v_mov_b32_e32 v2, v0
	v_mov_b32_e32 v3, v0
	v_mov_b32_e32 v4, v0
	v_mov_b32_e32 v5, v0
	v_mov_b32_e32 v6, v0
	v_mov_b32_e32 v7, v0
	v_mov_b32_e32 v16, v0
	v_mov_b32_e32 v17, v0
	v_mov_b32_e32 v18, v0
	v_mov_b32_e32 v19, v0
	v_mov_b32_e32 v20, v0
	v_mov_b32_e32 v21, v0
	v_mov_b32_e32 v22, v0
	v_mov_b32_e32 v23, v0
	v_mov_b32_e32 v36, v0
	v_mov_b32_e32 v37, v0
	v_mov_b32_e32 v38, v0
	v_mov_b32_e32 v39, v0
	v_mov_b32_e32 v52, v0
	v_mov_b32_e32 v53, v0
	v_mov_b32_e32 v54, v0
	v_mov_b32_e32 v55, v0
	v_mov_b32_e32 v64, v0
	v_mov_b32_e32 v65, v0
	v_mov_b32_e32 v66, v0
	v_mov_b32_e32 v67, v0
	v_mov_b32_e32 v68, v0
	v_mov_b32_e32 v69, v0
	v_mov_b32_e32 v70, v0
	v_mov_b32_e32 v71, v0
	v_mov_b32_e32 v8, v0
	v_mov_b32_e32 v9, v0
	v_mov_b32_e32 v10, v0
	v_mov_b32_e32 v11, v0
	v_mov_b32_e32 v12, v0
	v_mov_b32_e32 v13, v0
	v_mov_b32_e32 v14, v0
	v_mov_b32_e32 v15, v0
	v_mov_b32_e32 v24, v0
	v_mov_b32_e32 v25, v0
	v_mov_b32_e32 v26, v0
	v_mov_b32_e32 v27, v0
	v_mov_b32_e32 v28, v0
	v_mov_b32_e32 v29, v0
	v_mov_b32_e32 v30, v0
	v_mov_b32_e32 v31, v0
	v_mov_b32_e32 v56, v0
	v_mov_b32_e32 v57, v0
	v_mov_b32_e32 v58, v0
	v_mov_b32_e32 v59, v0
	v_mov_b32_e32 v60, v0
	v_mov_b32_e32 v61, v0
	v_mov_b32_e32 v62, v0
	v_mov_b32_e32 v63, v0
	v_mov_b32_e32 v72, v0
	v_mov_b32_e32 v73, v0
	v_mov_b32_e32 v74, v0
	v_mov_b32_e32 v75, v0
	v_mov_b32_e32 v76, v0
	v_mov_b32_e32 v77, v0
	v_mov_b32_e32 v78, v0
	v_mov_b32_e32 v79, v0
	v_mov_b32_e32 v80, v0
	v_mov_b32_e32 v81, v0
	v_mov_b32_e32 v82, v0
	v_mov_b32_e32 v83, v0
	v_mov_b32_e32 v84, v0
	v_mov_b32_e32 v85, v0
	v_mov_b32_e32 v86, v0
	v_mov_b32_e32 v87, v0
	v_mov_b32_e32 v96, v0
	v_mov_b32_e32 v97, v0
	v_mov_b32_e32 v98, v0
	v_mov_b32_e32 v99, v0
	v_mov_b32_e32 v100, v0
	v_mov_b32_e32 v101, v0
	v_mov_b32_e32 v102, v0
	v_mov_b32_e32 v103, v0
	v_mov_b32_e32 v112, v0
	v_mov_b32_e32 v113, v0
	v_mov_b32_e32 v114, v0
	v_mov_b32_e32 v115, v0
	v_mov_b32_e32 v116, v0
	v_mov_b32_e32 v117, v0
	v_mov_b32_e32 v118, v0
	v_mov_b32_e32 v119, v0
	v_mov_b32_e32 v128, v0
	v_mov_b32_e32 v129, v0
	v_mov_b32_e32 v130, v0
	v_mov_b32_e32 v131, v0
	v_mov_b32_e32 v132, v0
	v_mov_b32_e32 v133, v0
	v_mov_b32_e32 v134, v0
	v_mov_b32_e32 v135, v0
	v_mov_b32_e32 v88, v0
	v_mov_b32_e32 v89, v0
	v_mov_b32_e32 v90, v0
	v_mov_b32_e32 v91, v0
	v_mov_b32_e32 v92, v0
	v_mov_b32_e32 v93, v0
	v_mov_b32_e32 v94, v0
	v_mov_b32_e32 v95, v0
	v_mov_b32_e32 v104, v0
	v_mov_b32_e32 v105, v0
	v_mov_b32_e32 v106, v0
	v_mov_b32_e32 v107, v0
	v_mov_b32_e32 v108, v0
	v_mov_b32_e32 v109, v0
	v_mov_b32_e32 v110, v0
	v_mov_b32_e32 v111, v0
	v_mov_b32_e32 v120, v0
	v_mov_b32_e32 v121, v0
	v_mov_b32_e32 v122, v0
	v_mov_b32_e32 v123, v0
	v_mov_b32_e32 v124, v0
	v_mov_b32_e32 v125, v0
	v_mov_b32_e32 v126, v0
	v_mov_b32_e32 v127, v0
	v_mov_b32_e32 v136, v0
	v_mov_b32_e32 v137, v0
	v_mov_b32_e32 v138, v0
	v_mov_b32_e32 v139, v0
	v_mov_b32_e32 v140, v0
	v_mov_b32_e32 v141, v0
	v_mov_b32_e32 v142, v0
	v_mov_b32_e32 v143, v0
	s_andn2_b64 vcc, exec, s[0:1]
	s_cbranch_vccnz .LBB0_1161
